# GEMM LDS tile re-layout: each LDS-DMA piece now reads 8 rows x 128 B (full cache lines) instead of 16 rows x 64 B; new conflict-free XOR swizzle for ds_read_b128; all three GEMMs
# speedup vs baseline: 1.0099x; 1.0099x over previous
; #define PG8_STAGE(bufoff, gbase, voff) do { _Pragma("unroll") for (int _i = 0; _i < 2; ++_i) \
;         __builtin_amdgcn_global_load_lds((const unsigned*)((const char*)(gbase) + (voff)[_i]), (PG8_LAS unsigned*)(lds + (bufoff) + ldsw + _i * 8192), 16, 0, 0); } while (0)
; #define PG8_WAIT_V(n) asm volatile("s_waitcnt vmcnt(" #n ")" ::: "memory")
; #define PG8_BAR __builtin_amdgcn_s_barrier()
; template <class Epi, class Sched, bool ALIGN_EPI = false, bool SP2 = false>
; __device__ __forceinline__ void gemm_phase(PG8_LAS unsigned char* lds, const Gemm g, const Sched& S, const Epi& E) {
;     int tid_ = threadIdx.x; asm volatile("" : "+v"(tid_));
;     const int tid = tid_, wid = __builtin_amdgcn_readfirstlane(tid >> 6), lane = tid & 63, wr = wid >> 2, wc = wid & 3, fr = lane & 15, fq = lane >> 4;
;     const int K = g.K, nt = K / BK;
;     unsigned voffA[2], voffB[2];
; #pragma unroll
;     for (int i = 0; i < 2; ++i) { int R, C; stage_rc(tid * 16 + i * 8192, R, C); const int Rb = Epi::PERM ? ((R & ~31) + perm32(R & 31)) : R;
;         voffA[i] = (unsigned)(R * K + C) * 2u; voffB[i] = (unsigned)(Rb * K + C) * 2u; }
;     const size_t kstep = (size_t)(BK * 2);
;     const size_t hstep = (size_t)HALF * K * 2;
;     const size_t tstep = 2 * hstep;
;     const unsigned ldsw = (unsigned)wid * 1024u;
;     const int aoff = lds_byte(wr * 64 + fr, fq * 8), boff = lds_byte(wc * 32 + fr, fq * 8);
;     ...
;     const char* cA = (const char*)g.A + (size_t)(cur.pm & g.pm_mask) * tstep; const char* cB = (const char*)g.Bt + (size_t)cur.pn * tstep;
;     S.a_ready(cur);
;     if constexpr (SP2) {
;         PG8_STAGE(PG8_SB(0, 0), cB, voffB); PG8_STAGE(PG8_SB(0, 1), cB + hstep, voffB); PG8_STAGE(PG8_SA(0, 0), cA, voffA); PG8_STAGE(PG8_SA(0, 1), cA + hstep, voffA);
;         if (wr == 1) PG8_BAR;
;         PG8_WAIT_V(2); PG8_BAR;
.LBB0_77:
.LBB0_78:
	s_load_dwordx4 s[4:7], s[0:1], 0x90
	s_cmp_gt_u32 s85, 1
	s_mov_b64 s[12:13], -1
	s_waitcnt lgkmcnt(0)
	s_mov_b64 s[22:23], s[6:7]
	s_mov_b64 s[2:3], s[4:5]
	s_nop 0
	v_writelane_b32 v252, s2, 53
	s_nop 1
	v_writelane_b32 v252, s3, 54
	s_cbranch_scc0 .LBB0_758
	s_ashr_i32 s2, s85, 1
	s_cmp_lg_u32 s2, 17
	s_cbranch_scc0 .LBB0_751
	v_writelane_b32 v252, s2, 55
	s_add_i32 s2, s2, -1
	s_ashr_i32 s5, s2, 2
	s_and_b32 s6, s2, 3
	s_ashr_i32 s4, s2, 3
	s_and_b32 s2, s2, 4
	s_cmp_eq_u32 s2, 0
	v_writelane_b32 v252, s4, 56
	s_cselect_b64 s[12:13], -1, 0
	s_cmp_lg_u32 s2, 0
	v_writelane_b32 v252, s5, 57
	s_cselect_b64 s[2:3], -1, 0
	v_writelane_b32 v252, s2, 58
	s_mov_b64 s[16:17], -1
	s_nop 0
	v_writelane_b32 v252, s3, 59
	s_mul_i32 s3, s5, 0x18000
	s_mul_hi_i32 s2, s5, 0x18000
	s_add_u32 s3, s22, s3
	s_addc_u32 s2, s23, s2
	s_add_u32 s33, s3, 0x9080000
	s_addc_u32 s58, s2, 0
	s_add_u32 s70, s22, 0x96e4000
	s_addc_u32 s71, s23, 0
	v_writelane_b32 v252, s5, 60
	s_cmp_lt_i32 s6, 2
	v_writelane_b32 v252, s6, 61
	s_cbranch_scc1 .LBB0_264
	v_readlane_b32 s2, v252, 61
	s_cmp_gt_i32 s2, 2
	v_writelane_b32 v252, s33, 63
	v_writelane_b32 v247, s58, 0
	s_cbranch_scc0 .LBB0_103
	v_readlane_b32 s2, v253, 58
	v_mov_b32_e32 v16, v178
	v_readlane_b32 s3, v253, 59
	s_andn2_b64 vcc, exec, s[2:3]
	v_readfirstlane_b32 s2, v16
	s_cbranch_vccnz .LBB0_102
	v_lshlrev_b32_e32 v0, 4, v16
	v_add_u32_e32 v2, 0x2000, v0
	v_ashrrev_i32_e32 v3, 31, v2
	v_lshrrev_b32_e32 v3, 22, v3
	v_add_u32_e32 v3, v2, v3
	v_ashrrev_i32_e32 v10, 10, v3
	v_mul_i32_i24_e32 v3, 0x400, v10
	v_sub_u32_e32 v2, v2, v3
	v_lshrrev_b32_e32 v3, 4, v2
	v_bitop3_b32 v2, v3, v2, 32 bitop3:0x6c
	v_ashrrev_i32_e32 v3, 31, v2
	v_lshrrev_b32_e32 v3, 26, v3
	v_add_u32_e32 v3, v2, v3
	v_lshlrev_b32_e32 v4, 3, v10
	v_ashrrev_i32_e32 v11, 6, v3
	v_and_b32_e32 v4, -16, v4
	v_add_u32_e32 v4, v11, v4
	v_and_b32_e32 v5, 3, v11
	s_mov_b32 s7, 0xfffe0
	v_lshrrev_b32_e32 v6, 2, v4
	v_lshlrev_b32_e32 v7, 1, v4
	v_and_b32_e32 v3, 0xc0, v3
	v_and_or_b32 v5, v4, s7, v5
	v_and_b32_e32 v6, 4, v6
	v_and_b32_e32 v7, 24, v7
	v_sub_u32_e32 v2, v2, v3
	v_or3_b32 v5, v5, v6, v7
	v_lshlrev_b32_e32 v6, 5, v10
	v_ashrrev_i16_sdwa v2, v179, sext(v2) dst_sel:DWORD dst_unused:UNUSED_PAD src0_sel:DWORD src1_sel:BYTE_0
	v_and_b32_e32 v6, 32, v6
	v_bfe_i32 v12, v2, 0, 16
	v_add_lshl_u32 v2, v6, v12, 1
	v_and_b32_e32 v232, 63, v178
	v_lshrrev_b32_e32 v233, 6, v178
	v_lshrrev_b32_e32 v234, 3, v232
	v_and_b32_e32 v235, 7, v232
	v_bfe_u32 v246, v234, 1, 2
	v_and_b32_e32 v226, 1, v233
	v_lshl_or_b32 v246, v226, 2, v246
	v_xor_b32_e32 v235, v235, v246
	v_lshlrev_b32_e32 v235, 4, v235
	v_lshl_add_u32 v227, v233, 3, v234
	v_lshl_add_u32 v226, v227, 12, v235
	v_add_u32_e32 v227, 0x40000, v226
	v_and_b32_e32 v228, 1, v233
	v_lshrrev_b32_e32 v229, 2, v234
	v_lshl_add_u32 v228, v228, 1, v229
	v_bfe_u32 v229, v233, 1, 1
	v_and_b32_e32 v246, 3, v234
	v_lshl_or_b32 v229, v229, 2, v246
	v_lshl_add_u32 v228, v228, 3, v229
	v_lshrrev_b32_e32 v229, 2, v233
	v_lshl_add_u32 v228, v229, 5, v228
	v_lshl_add_u32 v228, v228, 12, v235
	v_add_u32_e32 v229, 0x40000, v228
	v_and_b32_e32 v246, 15, v232
	v_lshrrev_b32_e32 v234, 4, v232
	v_bfe_u32 v230, v246, 1, 2
	v_lshrrev_b32_e32 v231, 3, v246
	v_lshl_or_b32 v230, v231, 2, v230
	v_xor_b32_e32 v230, v230, v234
	v_lshlrev_b32_e32 v230, 4, v230
	v_lshl_add_u32 v230, v231, 10, v230
	v_and_b32_e32 v231, 7, v246
	v_lshl_add_u32 v230, v231, 7, v230
	v_and_b32_e32 v231, 3, v233
	v_lshl_add_u32 v231, v231, 12, v230
	v_lshrrev_b32_e32 v246, 2, v233
	v_lshl_add_u32 v230, v246, 13, v230
	v_xor_b32_e32 v248, 64, v230
	v_xor_b32_e32 v249, 64, v231
	v_mov_b32_e32 v146, v229
	v_mov_b32_e32 v148, v227
	v_bfe_i32 v2, v16, 27, 1
	v_lshrrev_b32_e32 v2, 22, v2
	v_add_u32_e32 v2, v0, v2
	v_and_b32_e32 v2, 0xfffffc00, v2
	v_sub_u32_e32 v0, v0, v2
	v_lshrrev_b32_e32 v2, 4, v0
	v_ashrrev_i32_e32 v3, 31, v16
	v_bitop3_b32 v0, v2, v0, 32 bitop3:0x6c
	v_lshrrev_b32_e32 v3, 26, v3
	s_and_b64 s[4:5], s[12:13], exec
	s_brev_b32 s3, 32
	v_ashrrev_i32_e32 v2, 31, v0
	v_add_u32_e32 v3, v16, v3
	s_cselect_b32 s3, s3, 0x8000000
	v_readlane_b32 s4, v252, 56
	v_lshrrev_b32_e32 v2, 26, v2
	v_ashrrev_i32_e32 v14, 6, v3
	s_add_u32 s3, s22, s3
	v_readlane_b32 s5, v252, 57
	v_add_u32_e32 v2, v0, v2
	v_lshlrev_b32_e32 v3, 3, v14
	s_addc_u32 s6, s23, 0
	s_mov_b32 s8, s4
	s_ashr_i32 s9, s4, 31
	v_writelane_b32 v252, s4, 56
	v_ashrrev_i32_e32 v13, 6, v2
	v_and_b32_e32 v3, -16, v3
	v_writelane_b32 v252, s5, 57
	s_lshl_b64 s[4:5], s[8:9], 23
	v_add_u32_e32 v3, v13, v3
	s_add_u32 s4, s3, s4
	v_and_b32_e32 v4, 3, v13
	v_lshrrev_b32_e32 v5, 2, v3
	v_lshlrev_b32_e32 v6, 1, v3
	v_and_b32_e32 v2, 0xc0, v2
	s_addc_u32 s5, s6, s5
	s_ashr_i32 s3, s2, 6
	v_and_or_b32 v4, v3, s7, v4
	v_and_b32_e32 v5, 4, v5
	v_and_b32_e32 v6, 24, v6
	v_sub_u32_e32 v0, v0, v2
	s_ashr_i32 s20, s2, 8
	s_lshl_b32 s6, s3, 10
	v_or3_b32 v4, v4, v5, v6
	v_lshlrev_b32_e32 v5, 5, v14
	v_ashrrev_i16_sdwa v0, v179, sext(v0) dst_sel:DWORD dst_unused:UNUSED_PAD src0_sel:DWORD src1_sel:BYTE_0
	v_readlane_b32 s8, v252, 10
	v_and_b32_e32 v5, 32, v5
	v_bfe_i32 v15, v0, 0, 16
	v_readlane_b32 s9, v252, 11
	s_add_u32 s24, s4, s8
	v_add_lshl_u32 v2, v5, v15, 1
	s_addc_u32 s25, s5, s9
	s_add_i32 s7, s6, 0
	v_mov_b32_e32 v0, v228
	s_add_i32 m0, s7, 0x10000
	v_mov_b32_e32 v150, v226
	global_load_lds_dwordx4 v0, s[24:25]
	s_add_i32 m0, s7, 0x12000
	s_add_u32 s8, s24, 0x80000
	global_load_lds_dwordx4 v146, s[24:25]
	s_addc_u32 s9, s25, 0
	s_add_i32 m0, s7, 0x14000
	v_mov_b32_e32 v147, v1
	global_load_lds_dwordx4 v0, s[8:9]
	s_add_i32 m0, s7, 0x16000
	v_mov_b32_e32 v151, v1
	global_load_lds_dwordx4 v146, s[8:9]
	v_readlane_b32 s8, v252, 19
	v_readlane_b32 s9, v252, 20
	s_add_u32 s50, s70, s8
	s_addc_u32 s51, s71, s9
	s_add_i32 s8, s7, 0x2000
	s_mov_b32 m0, s7
	s_add_u32 s12, s50, 0x80000
	global_load_lds_dwordx4 v150, s[50:51]
	s_mov_b32 m0, s8
	s_addc_u32 s13, s51, 0
	s_add_i32 s9, s7, 0x4000
	global_load_lds_dwordx4 v148, s[50:51]
	s_mov_b32 m0, s9
	s_add_i32 s30, s7, 0x6000
	global_load_lds_dwordx4 v150, s[12:13]
	s_mov_b32 m0, s30
	v_mov_b32_e32 v149, v1
	global_load_lds_dwordx4 v148, s[12:13]
	s_cmp_eq_u32 s20, 1
	v_lshl_add_u64 v[8:9], s[24:25], 0, v[0:1]
	v_lshl_add_u64 v[6:7], s[24:25], 0, v[146:147]
	v_lshl_add_u64 v[2:3], s[50:51], 0, v[150:151]
	s_cselect_b64 s[12:13], -1, 0
	s_cmp_lg_u32 s20, 1
	v_lshl_add_u64 v[4:5], s[50:51], 0, v[148:149]
	s_cbranch_scc1 .LBB0_85
	s_barrier
; #define PG8_STAGE(bufoff, gbase, voff) do { _Pragma("unroll") for (int _i = 0; _i < 2; ++_i) \
;         __builtin_amdgcn_global_load_lds((const unsigned*)((const char*)(gbase) + (voff)[_i]), (PG8_LAS unsigned*)(lds + (bufoff) + ldsw + _i * 8192), 16, 0, 0); } while (0)
; #define PG8_WAIT_V(n) asm volatile("s_waitcnt vmcnt(" #n ")" ::: "memory")
; #define PG8_BAR __builtin_amdgcn_s_barrier()
; template <class Epi, class Sched, bool ALIGN_EPI = false, bool SP2 = false>
; __device__ __forceinline__ void gemm_phase(PG8_LAS unsigned char* lds, const Gemm g, const Sched& S, const Epi& E) {
;     ...
;     const unsigned ldsw = (unsigned)wid * 1024u;
;     const int aoff = lds_byte(wr * 64 + fr, fq * 8), boff = lds_byte(wc * 32 + fr, fq * 8);
;     ...
;         PG8_STAGE(PG8_SB(1, 0), cB + kstep, voffB); PG8_STAGE(PG8_SA(1, 0), cA + kstep, voffA); PG8_STAGE(PG8_SB(1, 1), cB + hstep + kstep, voffB);
;         PG8_WAIT_V(6); PG8_BAR;
.LBB0_85:
	s_add_u32 s16, s22, 0xd6e4000
	s_addc_u32 s17, s23, 0
	v_lshrrev_b32_e32 v18, 1, v16
	s_add_u32 s54, s33, 0x4000
	v_and_b32_e32 v18, 24, v18
	s_addc_u32 s55, s58, 0
	v_and_b32_e32 v17, 15, v16
	v_lshlrev_b32_e32 v19, 1, v18
	v_lshlrev_b32_e32 v16, 2, v16
	s_lshl_b32 s3, s3, 5
	v_lshl_or_b32 v162, s20, 6, v17
	v_lshl_or_b32 v17, v17, 6, v19
	s_lshl_b32 s20, s20, 13
	v_and_b32_e32 v16, 32, v16
	s_and_b32 s3, s3, 0x60
	s_add_i32 m0, s7, 0x18000
	v_lshl_add_u64 v[8:9], v[8:9], 0, s[10:11]
	v_bitop3_b32 v19, v17, s20, v16 bitop3:0xde
	s_lshl_b32 s20, s3, 7
	s_waitcnt vmcnt(2)
	s_barrier
	global_load_lds_dwordx4 v[8:9], off
	v_lshl_add_u64 v[6:7], v[6:7], 0, s[10:11]
	s_add_i32 m0, s7, 0x1a000
	s_add_i32 s56, s7, 0x8000
	s_add_i32 s57, s7, 0xa000
	global_load_lds_dwordx4 v[6:7], off
	v_lshl_add_u64 v[2:3], v[2:3], 0, s[10:11]
	s_mov_b32 m0, s56
	s_add_u32 s26, s24, 0x80080
	global_load_lds_dwordx4 v[2:3], off
	v_lshl_add_u64 v[2:3], v[4:5], 0, s[10:11]
	s_mov_b32 m0, s57
	s_addc_u32 s27, s25, 0
	global_load_lds_dwordx4 v[2:3], off
	s_add_i32 m0, s7, 0x1c000
	v_lshl_add_u64 v[2:3], s[26:27], 0, v[0:1]
	global_load_lds_dwordx4 v[2:3], off
	v_lshl_add_u64 v[2:3], s[26:27], 0, v[146:147]
	s_add_i32 m0, s7, 0x1e000
	s_cmpk_lt_u32 s2, 0x100
	global_load_lds_dwordx4 v[2:3], off
	v_lshlrev_b32_e32 v2, 15, v10
	v_and_b32_e32 v2, 0xffff0000, v2
	v_lshl_add_u32 v2, v11, 12, v2
	v_and_b32_e32 v3, 1, v10
	v_lshl_or_b32 v2, v3, 6, v2
	v_mov_b32_e32 v152, v227
	v_lshlrev_b32_e32 v2, 15, v14
	v_and_b32_e32 v2, 0xffff0000, v2
	s_waitcnt vmcnt(6)
	v_lshl_add_u32 v2, v13, 12, v2
	v_and_b32_e32 v3, 1, v14
	v_or_b32_e32 v164, s3, v18
	v_lshl_or_b32 v2, v3, 6, v2
	v_readlane_b32 s2, v252, 17
	v_mov_b32_e32 v163, v231
	s_cselect_b64 s[26:27], -1, 0
	v_mov_b32_e32 v153, v1
	v_mov_b32_e32 v154, v226
	v_mov_b32_e32 v155, v1
	s_mov_b32 s58, 0
	v_mov_b32_e32 v165, v230
	v_readlane_b32 s60, v252, 9
	s_mov_b32 s59, s2
	s_barrier
	v_readlane_b32 s3, v252, 18
	s_branch .LBB0_88

; #define PG8_STAGE(bufoff, gbase, voff) do { _Pragma("unroll") for (int _i = 0; _i < 2; ++_i) \
;         __builtin_amdgcn_global_load_lds((const unsigned*)((const char*)(gbase) + (voff)[_i]), (PG8_LAS unsigned*)(lds + (bufoff) + ldsw + _i * 8192), 16, 0, 0); } while (0)
; #define PG8_LDA(dst, b, h) do { _Pragma("unroll") for (int m = 0; m < 4; ++m) _Pragma("unroll") for (int k = 0; k < 2; ++k) dst[m][k] = *(const PG8_LAS bf16x8*)(lds + PG8_SA(b, h) + aoff + m * 2048 + k * 1024); } while (0)
; #define PG8_LDB(dst, b, h) do { _Pragma("unroll") for (int n = 0; n < 2; ++n) _Pragma("unroll") for (int k = 0; k < 2; ++k) dst[n][k] = *(const PG8_LAS bf16x8*)(lds + PG8_SB(b, h) + boff + n * 2048 + k * 1024); } while (0)
; #define PG8_MMA(ai, bj, At, Bt) do { __builtin_amdgcn_s_setprio(1); _Pragma("unroll") for (int m = 0; m < 4; ++m) _Pragma("unroll") for (int n = 0; n < 2; ++n) _Pragma("unroll") for (int k = 0; k < 2; ++k) \
;         acc[ai][bj][m][n] = __builtin_amdgcn_mfma_f32_16x16x32_bf16(Bt[n][k], At[m][k], acc[ai][bj][m][n], 0, 0, 0); __builtin_amdgcn_s_setprio(0); } while (0)
; #define PG8_WAIT_V(n) asm volatile("s_waitcnt vmcnt(" #n ")" ::: "memory")
; #define PG8_WAIT_L(n) asm volatile("s_waitcnt lgkmcnt(" #n ")" ::: "memory")
; #define PG8_BAR __builtin_amdgcn_s_barrier()
; #define PG8_SCHED __builtin_amdgcn_sched_barrier(0)
; template <class Epi, class Sched, bool ALIGN_EPI = false, bool SP2 = false>
; __device__ __forceinline__ void gemm_phase(PG8_LAS unsigned char* lds, const Gemm g, const Sched& S, const Epi& E) {
;     ...
;             PG8_LDB(B0, 0, 0); PG8_LDB(B1, 0, 1); PG8_SCHED; PG8_LDA(At, 0, 0); PG8_STAGE(PG8_SA(1, 1), a1 + hstep, voffA);
;             PG8_WAIT_V(8); PG8_WAIT_L(0); PG8_BAR; PG8_MMA(0, 0, At, B0); PG8_MMA(0, 1, At, B1); PG8_BAR; PG8_SCHED;
;             PG8_LDA(At, 0, 1); PG8_STAGE(PG8_SB(0, 0), b2, voffB); PG8_STAGE(PG8_SB(0, 1), b2 + hstep, voffB); PG8_STAGE(PG8_SA(0, 0), a2, voffA);
;             PG8_WAIT_V(8); PG8_WAIT_L(0); PG8_BAR; PG8_MMA(1, 0, At, B0); PG8_MMA(1, 1, At, B1); PG8_BAR; PG8_SCHED;
.LBB0_95:
	s_add_u32 s2, s50, 0xfff80080
	s_addc_u32 s3, s51, -1
	s_add_i32 s20, 0, 0x10000
	s_cmp_eq_u32 s67, 28
	s_cselect_b32 s53, s45, s3
	s_cselect_b32 s52, s61, s2
	s_cselect_b32 s25, s43, s66
	s_cselect_b32 s24, s64, s65
	s_add_i32 s33, 0, 0x14000
	v_add_u32_e32 v126, s20, v163
	v_add_u32_e32 v250, s20, v249
	v_add_u32_e32 v160, s33, v163
	v_add_u32_e32 v251, s33, v249
	ds_read_b128 v[114:117], v126
	ds_read_b128 v[118:121], v250
	ds_read_b128 v[122:125], v126 offset:2048
	ds_read_b128 v[126:129], v250 offset:2048
	ds_read_b128 v[156:159], v160
	ds_read_b128 v[166:169], v251
	ds_read_b128 v[170:173], v160 offset:2048
	ds_read_b128 v[174:177], v251 offset:2048
	s_add_i32 m0, s7, 0xc000
	ds_read_b128 v[186:189], v165
	ds_read_b128 v[190:193], v248
	ds_read_b128 v[194:197], v165 offset:2048
	ds_read_b128 v[198:201], v248 offset:2048
	ds_read_b128 v[202:205], v165 offset:4096
	ds_read_b128 v[206:209], v248 offset:4096
	ds_read_b128 v[210:213], v165 offset:6144
	ds_read_b128 v[214:217], v248 offset:6144
	global_load_lds_dwordx4 v154, s[50:51]
	s_add_i32 m0, s7, 0xe000
	s_nop 0
	global_load_lds_dwordx4 v152, s[50:51]
	s_waitcnt vmcnt(8)
	s_waitcnt lgkmcnt(0)
	s_barrier
	s_setprio 1
	s_waitcnt lgkmcnt(0)
	v_mfma_f32_16x16x32_bf16 v[142:145], v[114:117], v[186:189], v[142:145]
	v_mfma_f32_16x16x32_bf16 v[138:141], v[122:125], v[186:189], v[138:141]
	v_mfma_f32_16x16x32_bf16 v[110:113], v[114:117], v[194:197], v[110:113]
	v_mfma_f32_16x16x32_bf16 v[106:109], v[122:125], v[194:197], v[106:109]
	v_mfma_f32_16x16x32_bf16 v[94:97], v[114:117], v[202:205], v[94:97]
	v_mfma_f32_16x16x32_bf16 v[90:93], v[122:125], v[202:205], v[90:93]
	v_mfma_f32_16x16x32_bf16 v[86:89], v[114:117], v[210:213], v[86:89]
	v_mfma_f32_16x16x32_bf16 v[78:81], v[122:125], v[210:213], v[78:81]
	v_mfma_f32_16x16x32_bf16 v[142:145], v[118:121], v[190:193], v[142:145]
	v_mfma_f32_16x16x32_bf16 v[138:141], v[126:129], v[190:193], v[138:141]
	v_mfma_f32_16x16x32_bf16 v[110:113], v[118:121], v[198:201], v[110:113]
	v_mfma_f32_16x16x32_bf16 v[106:109], v[126:129], v[198:201], v[106:109]
	v_mfma_f32_16x16x32_bf16 v[94:97], v[118:121], v[206:209], v[94:97]
	v_mfma_f32_16x16x32_bf16 v[90:93], v[126:129], v[206:209], v[90:93]
	v_mfma_f32_16x16x32_bf16 v[86:89], v[118:121], v[214:217], v[86:89]
	v_mfma_f32_16x16x32_bf16 v[78:81], v[126:129], v[214:217], v[78:81]
	s_setprio 0
	s_setprio 1
	v_mfma_f32_16x16x32_bf16 v[134:137], v[156:159], v[186:189], v[134:137]
	v_mfma_f32_16x16x32_bf16 v[130:133], v[170:173], v[186:189], v[130:133]
	v_mfma_f32_16x16x32_bf16 v[102:105], v[156:159], v[194:197], v[102:105]
	v_mfma_f32_16x16x32_bf16 v[98:101], v[170:173], v[194:197], v[98:101]
	v_mfma_f32_16x16x32_bf16 v[82:85], v[156:159], v[202:205], v[82:85]
	v_mfma_f32_16x16x32_bf16 v[74:77], v[170:173], v[202:205], v[74:77]
	v_mfma_f32_16x16x32_bf16 v[70:73], v[156:159], v[210:213], v[70:73]
	v_mfma_f32_16x16x32_bf16 v[66:69], v[170:173], v[210:213], v[66:69]
	v_mfma_f32_16x16x32_bf16 v[134:137], v[166:169], v[190:193], v[134:137]
	v_mfma_f32_16x16x32_bf16 v[130:133], v[174:177], v[190:193], v[130:133]
	v_mfma_f32_16x16x32_bf16 v[102:105], v[166:169], v[198:201], v[102:105]
	v_mfma_f32_16x16x32_bf16 v[98:101], v[174:177], v[198:201], v[98:101]
	v_mfma_f32_16x16x32_bf16 v[82:85], v[166:169], v[206:209], v[82:85]
	v_mfma_f32_16x16x32_bf16 v[74:77], v[174:177], v[206:209], v[74:77]
	v_mfma_f32_16x16x32_bf16 v[70:73], v[166:169], v[214:217], v[70:73]
	v_mfma_f32_16x16x32_bf16 v[66:69], v[174:177], v[214:217], v[66:69]
	s_setprio 0
	s_barrier
	s_add_i32 s2, s20, s6
	s_mov_b32 m0, s2
	ds_read_b128 v[186:189], v165 offset:16384
	ds_read_b128 v[190:193], v248 offset:16384
	ds_read_b128 v[194:197], v165 offset:18432
	ds_read_b128 v[198:201], v248 offset:18432
	ds_read_b128 v[202:205], v165 offset:20480
	ds_read_b128 v[206:209], v248 offset:20480
	ds_read_b128 v[210:213], v165 offset:22528
	ds_read_b128 v[214:217], v248 offset:22528
	global_load_lds_dwordx4 v0, s[24:25]
	s_add_i32 m0, s2, 0x2000
	s_add_u32 s2, s24, 0x80000
	s_addc_u32 s3, s25, 0
	s_add_i32 s20, s33, s6
	global_load_lds_dwordx4 v146, s[24:25]
	s_mov_b32 m0, s20
	s_nop 0
	global_load_lds_dwordx4 v0, s[2:3]
	s_add_i32 m0, s20, 0x2000
	s_nop 0
	global_load_lds_dwordx4 v146, s[2:3]
	s_mov_b32 m0, s7
	s_nop 0
	global_load_lds_dwordx4 v150, s[52:53]
	s_mov_b32 m0, s8
	s_nop 0
	global_load_lds_dwordx4 v148, s[52:53]
	s_waitcnt vmcnt(8)
	s_waitcnt lgkmcnt(0)
	s_barrier
	s_setprio 1
	s_waitcnt lgkmcnt(0)
	v_mfma_f32_16x16x32_bf16 v[62:65], v[114:117], v[186:189], v[62:65]
	v_mfma_f32_16x16x32_bf16 v[58:61], v[122:125], v[186:189], v[58:61]
	v_mfma_f32_16x16x32_bf16 v[54:57], v[114:117], v[194:197], v[54:57]
	v_mfma_f32_16x16x32_bf16 v[50:53], v[122:125], v[194:197], v[50:53]
	v_mfma_f32_16x16x32_bf16 v[38:41], v[114:117], v[202:205], v[38:41]
	v_mfma_f32_16x16x32_bf16 v[34:37], v[122:125], v[202:205], v[34:37]
	v_mfma_f32_16x16x32_bf16 v[22:25], v[114:117], v[210:213], v[22:25]
	v_mfma_f32_16x16x32_bf16 v[18:21], v[122:125], v[210:213], v[18:21]
	v_mfma_f32_16x16x32_bf16 v[62:65], v[118:121], v[190:193], v[62:65]
	v_mfma_f32_16x16x32_bf16 v[58:61], v[126:129], v[190:193], v[58:61]
	v_mfma_f32_16x16x32_bf16 v[54:57], v[118:121], v[198:201], v[54:57]
	v_mfma_f32_16x16x32_bf16 v[50:53], v[126:129], v[198:201], v[50:53]
	v_mfma_f32_16x16x32_bf16 v[38:41], v[118:121], v[206:209], v[38:41]
	v_mfma_f32_16x16x32_bf16 v[34:37], v[126:129], v[206:209], v[34:37]
	v_mfma_f32_16x16x32_bf16 v[22:25], v[118:121], v[214:217], v[22:25]
	v_mfma_f32_16x16x32_bf16 v[18:21], v[126:129], v[214:217], v[18:21]
	s_setprio 0
	s_setprio 1
	v_mfma_f32_16x16x32_bf16 v[46:49], v[156:159], v[186:189], v[46:49]
	v_mfma_f32_16x16x32_bf16 v[42:45], v[170:173], v[186:189], v[42:45]
	v_mfma_f32_16x16x32_bf16 v[30:33], v[156:159], v[194:197], v[30:33]
	v_mfma_f32_16x16x32_bf16 v[26:29], v[170:173], v[194:197], v[26:29]
	v_mfma_f32_16x16x32_bf16 v[14:17], v[156:159], v[202:205], v[14:17]
	v_mfma_f32_16x16x32_bf16 v[10:13], v[170:173], v[202:205], v[10:13]
	v_mfma_f32_16x16x32_bf16 v[6:9], v[156:159], v[210:213], v[6:9]
	v_mfma_f32_16x16x32_bf16 v[2:5], v[170:173], v[210:213], v[2:5]
	v_mfma_f32_16x16x32_bf16 v[46:49], v[166:169], v[190:193], v[46:49]
	v_mfma_f32_16x16x32_bf16 v[42:45], v[174:177], v[190:193], v[42:45]
	v_mfma_f32_16x16x32_bf16 v[30:33], v[166:169], v[198:201], v[30:33]
	v_mfma_f32_16x16x32_bf16 v[26:29], v[174:177], v[198:201], v[26:29]
	v_mfma_f32_16x16x32_bf16 v[14:17], v[166:169], v[206:209], v[14:17]
	v_mfma_f32_16x16x32_bf16 v[10:13], v[174:177], v[206:209], v[10:13]
	v_mfma_f32_16x16x32_bf16 v[6:9], v[166:169], v[214:217], v[6:9]
	v_mfma_f32_16x16x32_bf16 v[2:5], v[174:177], v[214:217], v[2:5]
	s_setprio 0
	s_barrier
; #define PG8_STAGE(bufoff, gbase, voff) do { _Pragma("unroll") for (int _i = 0; _i < 2; ++_i) \
;         __builtin_amdgcn_global_load_lds((const unsigned*)((const char*)(gbase) + (voff)[_i]), (PG8_LAS unsigned*)(lds + (bufoff) + ldsw + _i * 8192), 16, 0, 0); } while (0)
; #define PG8_LDA(dst, b, h) do { _Pragma("unroll") for (int m = 0; m < 4; ++m) _Pragma("unroll") for (int k = 0; k < 2; ++k) dst[m][k] = *(const PG8_LAS bf16x8*)(lds + PG8_SA(b, h) + aoff + m * 2048 + k * 1024); } while (0)
; #define PG8_LDB(dst, b, h) do { _Pragma("unroll") for (int n = 0; n < 2; ++n) _Pragma("unroll") for (int k = 0; k < 2; ++k) dst[n][k] = *(const PG8_LAS bf16x8*)(lds + PG8_SB(b, h) + boff + n * 2048 + k * 1024); } while (0)
; #define PG8_MMA(ai, bj, At, Bt) do { __builtin_amdgcn_s_setprio(1); _Pragma("unroll") for (int m = 0; m < 4; ++m) _Pragma("unroll") for (int n = 0; n < 2; ++n) _Pragma("unroll") for (int k = 0; k < 2; ++k) \
;         acc[ai][bj][m][n] = __builtin_amdgcn_mfma_f32_16x16x32_bf16(Bt[n][k], At[m][k], acc[ai][bj][m][n], 0, 0, 0); __builtin_amdgcn_s_setprio(0); } while (0)
; #define PG8_WAIT_V(n) asm volatile("s_waitcnt vmcnt(" #n ")" ::: "memory")
; #define PG8_WAIT_L(n) asm volatile("s_waitcnt lgkmcnt(" #n ")" ::: "memory")
; #define PG8_BAR __builtin_amdgcn_s_barrier()
; #define PG8_SCHED __builtin_amdgcn_sched_barrier(0)
; template <class Epi, class Sched, bool ALIGN_EPI = false, bool SP2 = false>
; __device__ __forceinline__ void gemm_phase(PG8_LAS unsigned char* lds, const Gemm g, const Sched& S, const Epi& E) {
;     ...
;         for (int t = 0; t < nt; t += 2) {
;     ...
;             PG8_LDB(B0, 1, 0); PG8_LDB(B1, 1, 1); PG8_SCHED; PG8_LDA(At, 1, 0); PG8_STAGE(PG8_SA(0, 1), a2 + hstep, voffA);
;             PG8_WAIT_V(8); PG8_WAIT_L(0); PG8_BAR; PG8_MMA(0, 0, At, B0); PG8_MMA(0, 1, At, B1); PG8_BAR; PG8_SCHED;
;             PG8_LDA(At, 1, 1); PG8_STAGE(PG8_SB(1, 0), b3, voffB); PG8_STAGE(PG8_SB(1, 1), b3 + hstep, voffB); PG8_STAGE(PG8_SA(1, 0), a3, voffA);
;             PG8_WAIT_V(8); PG8_WAIT_L(0); PG8_BAR; PG8_MMA(1, 0, At, B0); PG8_MMA(1, 1, At, B1); PG8_BAR; PG8_SCHED;
	s_add_i32 s20, 0, 0x18000
	s_add_i32 s33, 0, 0x1c000
	v_add_u32_e32 v126, s20, v163
	v_add_u32_e32 v250, s20, v249
	v_add_u32_e32 v174, s33, v163
	v_add_u32_e32 v251, s33, v249
	ds_read_b128 v[114:117], v126
	ds_read_b128 v[118:121], v250
	ds_read_b128 v[122:125], v126 offset:2048
	ds_read_b128 v[126:129], v250 offset:2048
	ds_read_b128 v[156:159], v174
	ds_read_b128 v[166:169], v251
	ds_read_b128 v[170:173], v174 offset:2048
	ds_read_b128 v[174:177], v251 offset:2048
	s_add_u32 s2, s52, 0x80000
	s_addc_u32 s3, s53, 0
	s_mov_b32 m0, s9
	ds_read_b128 v[186:189], v165 offset:32768
	ds_read_b128 v[190:193], v248 offset:32768
	ds_read_b128 v[194:197], v165 offset:34816
	ds_read_b128 v[198:201], v248 offset:34816
	ds_read_b128 v[202:205], v165 offset:36864
	ds_read_b128 v[206:209], v248 offset:36864
	ds_read_b128 v[210:213], v165 offset:38912
	ds_read_b128 v[214:217], v248 offset:38912
	global_load_lds_dwordx4 v150, s[2:3]
	s_mov_b32 m0, s30
	s_nop 0
	global_load_lds_dwordx4 v148, s[2:3]
	s_waitcnt vmcnt(8)
	s_waitcnt lgkmcnt(0)
	s_barrier
	s_setprio 1
	s_waitcnt lgkmcnt(0)
	v_mfma_f32_16x16x32_bf16 v[142:145], v[114:117], v[186:189], v[142:145]
	v_mfma_f32_16x16x32_bf16 v[138:141], v[122:125], v[186:189], v[138:141]
	v_mfma_f32_16x16x32_bf16 v[110:113], v[114:117], v[194:197], v[110:113]
	v_mfma_f32_16x16x32_bf16 v[106:109], v[122:125], v[194:197], v[106:109]
	v_mfma_f32_16x16x32_bf16 v[94:97], v[114:117], v[202:205], v[94:97]
	v_mfma_f32_16x16x32_bf16 v[90:93], v[122:125], v[202:205], v[90:93]
	v_mfma_f32_16x16x32_bf16 v[86:89], v[114:117], v[210:213], v[86:89]
	v_mfma_f32_16x16x32_bf16 v[78:81], v[122:125], v[210:213], v[78:81]
	v_mfma_f32_16x16x32_bf16 v[142:145], v[118:121], v[190:193], v[142:145]
	v_mfma_f32_16x16x32_bf16 v[138:141], v[126:129], v[190:193], v[138:141]
	v_mfma_f32_16x16x32_bf16 v[110:113], v[118:121], v[198:201], v[110:113]
	v_mfma_f32_16x16x32_bf16 v[106:109], v[126:129], v[198:201], v[106:109]
	v_mfma_f32_16x16x32_bf16 v[94:97], v[118:121], v[206:209], v[94:97]
	v_mfma_f32_16x16x32_bf16 v[90:93], v[126:129], v[206:209], v[90:93]
	v_mfma_f32_16x16x32_bf16 v[86:89], v[118:121], v[214:217], v[86:89]
	v_mfma_f32_16x16x32_bf16 v[78:81], v[126:129], v[214:217], v[78:81]
	s_setprio 0
	s_setprio 1
	v_mfma_f32_16x16x32_bf16 v[134:137], v[156:159], v[186:189], v[134:137]
	v_mfma_f32_16x16x32_bf16 v[130:133], v[170:173], v[186:189], v[130:133]
	v_mfma_f32_16x16x32_bf16 v[102:105], v[156:159], v[194:197], v[102:105]
	v_mfma_f32_16x16x32_bf16 v[98:101], v[170:173], v[194:197], v[98:101]
	v_mfma_f32_16x16x32_bf16 v[82:85], v[156:159], v[202:205], v[82:85]
	v_mfma_f32_16x16x32_bf16 v[74:77], v[170:173], v[202:205], v[74:77]
	v_mfma_f32_16x16x32_bf16 v[70:73], v[156:159], v[210:213], v[70:73]
	v_mfma_f32_16x16x32_bf16 v[66:69], v[170:173], v[210:213], v[66:69]
	v_mfma_f32_16x16x32_bf16 v[134:137], v[166:169], v[190:193], v[134:137]
	v_mfma_f32_16x16x32_bf16 v[130:133], v[174:177], v[190:193], v[130:133]
	v_mfma_f32_16x16x32_bf16 v[102:105], v[166:169], v[198:201], v[102:105]
	v_mfma_f32_16x16x32_bf16 v[98:101], v[174:177], v[198:201], v[98:101]
	v_mfma_f32_16x16x32_bf16 v[82:85], v[166:169], v[206:209], v[82:85]
	v_mfma_f32_16x16x32_bf16 v[74:77], v[174:177], v[206:209], v[74:77]
	v_mfma_f32_16x16x32_bf16 v[70:73], v[166:169], v[214:217], v[70:73]
	v_mfma_f32_16x16x32_bf16 v[66:69], v[174:177], v[214:217], v[66:69]
	s_setprio 0
	s_barrier
	s_add_i32 s2, s20, s6
	s_add_i32 m0, s2, 0xffffff80
	ds_read_b128 v[186:189], v165 offset:49152
	ds_read_b128 v[190:193], v248 offset:49152
	ds_read_b128 v[194:197], v165 offset:51200
	ds_read_b128 v[198:201], v248 offset:51200
	ds_read_b128 v[202:205], v165 offset:53248
	ds_read_b128 v[206:209], v248 offset:53248
	ds_read_b128 v[210:213], v165 offset:55296
	ds_read_b128 v[214:217], v248 offset:55296
	global_load_lds_dwordx4 v0, s[24:25] offset:128
	s_add_i32 m0, s2, 0x1f80
	s_add_u32 s2, s24, 0x80080
	s_addc_u32 s3, s25, 0
	s_add_i32 s20, s33, s6
	global_load_lds_dwordx4 v146, s[24:25] offset:128
	s_mov_b32 m0, s20
	s_nop 0
	global_load_lds_dwordx4 v0, s[2:3]
	s_add_i32 m0, s20, 0x2000
	s_nop 0
	global_load_lds_dwordx4 v146, s[2:3]
	s_add_i32 m0, s56, 0xffffff80
	s_nop 0
	global_load_lds_dwordx4 v150, s[52:53] offset:128
	s_add_i32 m0, s57, 0xffffff80
	s_nop 0
	global_load_lds_dwordx4 v148, s[52:53] offset:128
	s_waitcnt vmcnt(8)
	s_waitcnt lgkmcnt(0)
	s_barrier
	s_setprio 1
	s_waitcnt lgkmcnt(0)
	v_mfma_f32_16x16x32_bf16 v[62:65], v[114:117], v[186:189], v[62:65]
	v_mfma_f32_16x16x32_bf16 v[58:61], v[122:125], v[186:189], v[58:61]
	v_mfma_f32_16x16x32_bf16 v[54:57], v[114:117], v[194:197], v[54:57]
	v_mfma_f32_16x16x32_bf16 v[50:53], v[122:125], v[194:197], v[50:53]
	v_mfma_f32_16x16x32_bf16 v[38:41], v[114:117], v[202:205], v[38:41]
	v_mfma_f32_16x16x32_bf16 v[34:37], v[122:125], v[202:205], v[34:37]
	v_mfma_f32_16x16x32_bf16 v[22:25], v[114:117], v[210:213], v[22:25]
	v_mfma_f32_16x16x32_bf16 v[18:21], v[122:125], v[210:213], v[18:21]
	v_mfma_f32_16x16x32_bf16 v[62:65], v[118:121], v[190:193], v[62:65]
	v_mfma_f32_16x16x32_bf16 v[58:61], v[126:129], v[190:193], v[58:61]
	v_mfma_f32_16x16x32_bf16 v[54:57], v[118:121], v[198:201], v[54:57]
	v_mfma_f32_16x16x32_bf16 v[50:53], v[126:129], v[198:201], v[50:53]
	v_mfma_f32_16x16x32_bf16 v[38:41], v[118:121], v[206:209], v[38:41]
	v_mfma_f32_16x16x32_bf16 v[34:37], v[126:129], v[206:209], v[34:37]
	v_mfma_f32_16x16x32_bf16 v[22:25], v[118:121], v[214:217], v[22:25]
	v_mfma_f32_16x16x32_bf16 v[18:21], v[126:129], v[214:217], v[18:21]
	s_setprio 0
	s_setprio 1
	v_mfma_f32_16x16x32_bf16 v[46:49], v[156:159], v[186:189], v[46:49]
	v_mfma_f32_16x16x32_bf16 v[42:45], v[170:173], v[186:189], v[42:45]
	v_mfma_f32_16x16x32_bf16 v[30:33], v[156:159], v[194:197], v[30:33]
	v_mfma_f32_16x16x32_bf16 v[26:29], v[170:173], v[194:197], v[26:29]
	v_mfma_f32_16x16x32_bf16 v[14:17], v[156:159], v[202:205], v[14:17]
	v_mfma_f32_16x16x32_bf16 v[10:13], v[170:173], v[202:205], v[10:13]
	v_mfma_f32_16x16x32_bf16 v[6:9], v[156:159], v[210:213], v[6:9]
	v_mfma_f32_16x16x32_bf16 v[2:5], v[170:173], v[210:213], v[2:5]
	v_mfma_f32_16x16x32_bf16 v[46:49], v[166:169], v[190:193], v[46:49]
	v_mfma_f32_16x16x32_bf16 v[42:45], v[174:177], v[190:193], v[42:45]
	v_mfma_f32_16x16x32_bf16 v[30:33], v[166:169], v[198:201], v[30:33]
	v_mfma_f32_16x16x32_bf16 v[26:29], v[174:177], v[198:201], v[26:29]
	v_mfma_f32_16x16x32_bf16 v[14:17], v[166:169], v[206:209], v[14:17]
	v_mfma_f32_16x16x32_bf16 v[10:13], v[174:177], v[206:209], v[10:13]
	v_mfma_f32_16x16x32_bf16 v[6:9], v[166:169], v[214:217], v[6:9]
	v_mfma_f32_16x16x32_bf16 v[2:5], v[174:177], v[214:217], v[2:5]
	s_setprio 0
	s_barrier
	s_add_i32 s67, s67, 2
	s_add_u32 s65, s65, 0x100
	s_addc_u32 s66, s66, 0
	s_add_u32 s50, s50, 0x100
	s_addc_u32 s51, s51, 0
	s_cmp_gt_u32 s67, 29
	s_cbranch_scc0 .LBB0_95
	s_and_b64 vcc, exec, s[26:27]
	s_cbranch_vccz .LBB0_98
	s_barrier

; #define PG8_STAGE(bufoff, gbase, voff) do { _Pragma("unroll") for (int _i = 0; _i < 2; ++_i) \
;         __builtin_amdgcn_global_load_lds((const unsigned*)((const char*)(gbase) + (voff)[_i]), (PG8_LAS unsigned*)(lds + (bufoff) + ldsw + _i * 8192), 16, 0, 0); } while (0)
; #define PG8_WAIT_V(n) asm volatile("s_waitcnt vmcnt(" #n ")" ::: "memory")
; #define PG8_BAR __builtin_amdgcn_s_barrier()
; template <class Epi, class Sched, bool ALIGN_EPI = false, bool SP2 = false>
; __device__ __forceinline__ void gemm_phase(PG8_LAS unsigned char* lds, const Gemm g, const Sched& S, const Epi& E) {
;     int tid_ = threadIdx.x; asm volatile("" : "+v"(tid_));
;     const int tid = tid_, wid = __builtin_amdgcn_readfirstlane(tid >> 6), lane = tid & 63, wr = wid >> 2, wc = wid & 3, fr = lane & 15, fq = lane >> 4;
;     const int K = g.K, nt = K / BK;
;     unsigned voffA[2], voffB[2];
; #pragma unroll
;     for (int i = 0; i < 2; ++i) { int R, C; stage_rc(tid * 16 + i * 8192, R, C); const int Rb = Epi::PERM ? ((R & ~31) + perm32(R & 31)) : R;
;         voffA[i] = (unsigned)(R * K + C) * 2u; voffB[i] = (unsigned)(Rb * K + C) * 2u; }
;     const size_t kstep = (size_t)(BK * 2);
;     const size_t hstep = (size_t)HALF * K * 2;
;     const size_t tstep = 2 * hstep;
;     const unsigned ldsw = (unsigned)wid * 1024u;
;     const int aoff = lds_byte(wr * 64 + fr, fq * 8), boff = lds_byte(wc * 32 + fr, fq * 8);
;     ...
;     const char* cA = (const char*)g.A + (size_t)(cur.pm & g.pm_mask) * tstep; const char* cB = (const char*)g.Bt + (size_t)cur.pn * tstep;
;     S.a_ready(cur);
;     if constexpr (SP2) {
;         PG8_STAGE(PG8_SB(0, 0), cB, voffB); PG8_STAGE(PG8_SB(0, 1), cB + hstep, voffB); PG8_STAGE(PG8_SA(0, 0), cA, voffA); PG8_STAGE(PG8_SA(0, 1), cA + hstep, voffA);
;         if (wr == 1) PG8_BAR;
;         PG8_WAIT_V(2); PG8_BAR;
.LBB0_298:
	s_and_b64 vcc, exec, s[12:13]
	s_cbranch_vccz .LBB0_750
	v_readlane_b32 s2, v252, 58
	v_readlane_b32 s3, v252, 59
	s_mov_b64 s[12:13], -1
	s_and_b64 vcc, exec, s[2:3]
	s_cbranch_vccz .LBB0_337
	v_readlane_b32 s2, v252, 2
	v_mov_b32_e32 v15, v178
	v_readlane_b32 s3, v252, 3
	s_andn2_b64 vcc, exec, s[2:3]
	v_readfirstlane_b32 s2, v15
	s_cbranch_vccnz .LBB0_336
	v_lshlrev_b32_e32 v2, 4, v15
	v_add_u32_e32 v3, 0x2000, v2
	v_ashrrev_i32_e32 v0, 31, v3
	v_lshrrev_b32_e32 v0, 22, v0
	v_add_u32_e32 v0, v3, v0
	v_ashrrev_i32_e32 v0, 10, v0
	v_mul_i32_i24_e32 v4, 0x400, v0
	v_sub_u32_e32 v3, v3, v4
	v_lshrrev_b32_e32 v4, 4, v3
	v_bitop3_b32 v3, v4, v3, 32 bitop3:0x6c
	v_ashrrev_i32_e32 v4, 31, v3
	v_writelane_b32 v252, s88, 61
	v_lshrrev_b32_e32 v4, 26, v4
	v_add_u32_e32 v4, v3, v4
	v_writelane_b32 v252, s89, 62
	v_lshlrev_b32_e32 v5, 3, v0
	v_readlane_b32 s4, v252, 56
	v_ashrrev_i32_e32 v10, 6, v4
	v_and_b32_e32 v5, -16, v5
	v_readlane_b32 s5, v252, 57
	v_add_u32_e32 v5, v10, v5
	v_and_b32_e32 v6, 3, v10
	s_mov_b32 s5, 0xfffe0
	v_lshrrev_b32_e32 v7, 2, v5
	v_lshlrev_b32_e32 v8, 1, v5
	v_and_b32_e32 v4, 0xc0, v4
	v_and_or_b32 v6, v5, s5, v6
	v_and_b32_e32 v7, 4, v7
	v_and_b32_e32 v8, 24, v8
	v_sub_u32_e32 v3, v3, v4
	v_or3_b32 v6, v6, v7, v8
	v_lshlrev_b32_e32 v7, 5, v0
	v_ashrrev_i16_sdwa v3, v179, sext(v3) dst_sel:DWORD dst_unused:UNUSED_PAD src0_sel:DWORD src1_sel:BYTE_0
	v_and_b32_e32 v7, 32, v7
	v_bfe_i32 v11, v3, 0, 16
	v_add_lshl_u32 v3, v7, v11, 1
	v_and_b32_e32 v232, 63, v178
	v_lshrrev_b32_e32 v233, 6, v178
	v_lshrrev_b32_e32 v234, 3, v232
	v_and_b32_e32 v235, 7, v232
	v_bfe_u32 v246, v234, 1, 2
	v_and_b32_e32 v226, 1, v233
	v_lshl_or_b32 v246, v226, 2, v246
	v_xor_b32_e32 v235, v235, v246
	v_lshlrev_b32_e32 v235, 4, v235
	v_lshl_add_u32 v227, v233, 3, v234
	v_lshl_add_u32 v226, v227, 12, v235
	v_add_u32_e32 v227, 0x40000, v226
	v_and_b32_e32 v228, 1, v233
	v_lshrrev_b32_e32 v229, 2, v234
	v_lshl_add_u32 v228, v228, 1, v229
	v_bfe_u32 v229, v233, 1, 1
	v_and_b32_e32 v246, 3, v234
	v_lshl_or_b32 v229, v229, 2, v246
	v_lshl_add_u32 v228, v228, 3, v229
	v_lshrrev_b32_e32 v229, 2, v233
	v_lshl_add_u32 v228, v229, 5, v228
	v_lshl_add_u32 v228, v228, 12, v235
	v_add_u32_e32 v229, 0x40000, v228
	v_and_b32_e32 v246, 15, v232
	v_lshrrev_b32_e32 v234, 4, v232
	v_bfe_u32 v230, v246, 1, 2
	v_lshrrev_b32_e32 v231, 3, v246
	v_lshl_or_b32 v230, v231, 2, v230
	v_xor_b32_e32 v230, v230, v234
	v_lshlrev_b32_e32 v230, 4, v230
	v_lshl_add_u32 v230, v231, 10, v230
	v_and_b32_e32 v231, 7, v246
	v_lshl_add_u32 v230, v231, 7, v230
	v_and_b32_e32 v231, 3, v233
	v_lshl_add_u32 v231, v231, 12, v230
	v_lshrrev_b32_e32 v246, 2, v233
	v_lshl_add_u32 v230, v246, 13, v230
	v_xor_b32_e32 v248, 64, v230
	v_xor_b32_e32 v249, 64, v231
	v_mov_b32_e32 v130, v229
	v_mov_b32_e32 v132, v227
	v_bfe_i32 v3, v15, 27, 1
	v_lshrrev_b32_e32 v3, 22, v3
	v_add_u32_e32 v3, v2, v3
	v_and_b32_e32 v3, 0xfffffc00, v3
	v_sub_u32_e32 v2, v2, v3
	v_lshrrev_b32_e32 v3, 4, v2
	v_ashrrev_i32_e32 v4, 31, v15
	v_bitop3_b32 v2, v3, v2, 32 bitop3:0x6c
	v_lshrrev_b32_e32 v4, 26, v4
	v_ashrrev_i32_e32 v3, 31, v2
	v_add_u32_e32 v4, v15, v4
	v_lshrrev_b32_e32 v3, 26, v3
	v_ashrrev_i32_e32 v13, 6, v4
	s_mul_hi_i32 s3, s4, 0x1800000
	s_mul_i32 s4, s4, 0x1800000
	v_add_u32_e32 v3, v2, v3
	v_lshlrev_b32_e32 v4, 3, v13
	s_add_u32 s4, s22, s4
	v_ashrrev_i32_e32 v12, 6, v3
	v_and_b32_e32 v4, -16, v4
	s_addc_u32 s3, s23, s3
	v_add_u32_e32 v4, v12, v4
	s_add_u32 s58, s4, 0x5000000
	v_and_b32_e32 v5, 3, v12
	v_lshrrev_b32_e32 v6, 2, v4
	v_lshlrev_b32_e32 v7, 1, v4
	v_and_b32_e32 v3, 0xc0, v3
	s_addc_u32 s59, s3, 0
	s_ashr_i32 s4, s2, 6
	v_and_or_b32 v5, v4, s5, v5
	v_and_b32_e32 v6, 4, v6
	v_and_b32_e32 v7, 24, v7
	v_sub_u32_e32 v2, v2, v3
	s_ashr_i32 s3, s2, 8
	s_lshl_b32 s64, s4, 10
	v_or3_b32 v5, v5, v6, v7
	v_lshlrev_b32_e32 v6, 5, v13
	v_ashrrev_i16_sdwa v2, v179, sext(v2) dst_sel:DWORD dst_unused:UNUSED_PAD src0_sel:DWORD src1_sel:BYTE_0
	v_readlane_b32 s6, v252, 12
	v_and_b32_e32 v6, 32, v6
	v_bfe_i32 v14, v2, 0, 16
	v_readlane_b32 s7, v252, 13
	s_add_u32 s12, s58, s6
	v_add_lshl_u32 v2, v6, v14, 1
	s_addc_u32 s13, s59, s7
	s_add_i32 s65, s64, 0
	v_mov_b32_e32 v134, v228
	s_add_i32 m0, s65, 0x10000
	v_mov_b32_e32 v136, v226
	global_load_lds_dwordx4 v134, s[12:13]
	s_add_i32 m0, s65, 0x12000
	s_add_u32 s6, s12, 0x80000
	global_load_lds_dwordx4 v130, s[12:13]
	s_addc_u32 s7, s13, 0
	s_add_i32 m0, s65, 0x14000
	v_mov_b32_e32 v135, v1
	global_load_lds_dwordx4 v134, s[6:7]
	s_add_i32 m0, s65, 0x16000
	v_mov_b32_e32 v131, v1
	global_load_lds_dwordx4 v130, s[6:7]
	v_readlane_b32 s6, v252, 23
	v_readlane_b32 s7, v252, 24
	s_add_u32 s24, s70, s6
	s_addc_u32 s25, s71, s7
	s_add_i32 s66, s65, 0x2000
	s_mov_b32 m0, s65
	s_add_u32 s6, s24, 0x80000
	global_load_lds_dwordx4 v136, s[24:25]
	s_mov_b32 m0, s66
	s_addc_u32 s7, s25, 0
	s_add_i32 s67, s65, 0x4000
	global_load_lds_dwordx4 v132, s[24:25]
	s_mov_b32 m0, s67
	s_add_i32 s72, s65, 0x6000
	global_load_lds_dwordx4 v136, s[6:7]
	s_mov_b32 m0, s72
	v_mov_b32_e32 v137, v1
	global_load_lds_dwordx4 v132, s[6:7]
	v_mov_b32_e32 v133, v1
	s_cmp_eq_u32 s3, 1
	v_lshl_add_u64 v[8:9], s[12:13], 0, v[134:135]
	v_lshl_add_u64 v[6:7], s[12:13], 0, v[130:131]
	v_lshl_add_u64 v[2:3], s[24:25], 0, v[136:137]
	s_cselect_b64 s[16:17], -1, 0
	s_cmp_lg_u32 s3, 1
	v_lshl_add_u64 v[4:5], s[24:25], 0, v[132:133]
	s_cbranch_scc1 .LBB0_303
	s_barrier
; #define PG8_STAGE(bufoff, gbase, voff) do { _Pragma("unroll") for (int _i = 0; _i < 2; ++_i) \
;         __builtin_amdgcn_global_load_lds((const unsigned*)((const char*)(gbase) + (voff)[_i]), (PG8_LAS unsigned*)(lds + (bufoff) + ldsw + _i * 8192), 16, 0, 0); } while (0)
; #define PG8_WAIT_V(n) asm volatile("s_waitcnt vmcnt(" #n ")" ::: "memory")
; #define PG8_BAR __builtin_amdgcn_s_barrier()
; template <class Epi, class Sched, bool ALIGN_EPI = false, bool SP2 = false>
; __device__ __forceinline__ void gemm_phase(PG8_LAS unsigned char* lds, const Gemm g, const Sched& S, const Epi& E) {
;     ...
;     const unsigned ldsw = (unsigned)wid * 1024u;
;     const int aoff = lds_byte(wr * 64 + fr, fq * 8), boff = lds_byte(wc * 32 + fr, fq * 8);
;     ...
;         PG8_STAGE(PG8_SB(1, 0), cB + kstep, voffB); PG8_STAGE(PG8_SA(1, 0), cA + kstep, voffA); PG8_STAGE(PG8_SB(1, 1), cB + hstep + kstep, voffB);
;         PG8_WAIT_V(6); PG8_BAR;
.LBB0_303:
	s_add_u32 s44, s22, 0xd6e4000
	s_addc_u32 s45, s23, 0
	s_add_u32 s46, s22, 0x116e4000
	s_addc_u32 s47, s23, 0
	v_bfe_u32 v17, v15, 4, 2
	s_add_u32 s48, s22, 0x92e4000
	v_and_b32_e32 v16, 15, v15
	v_lshlrev_b32_e32 v19, 4, v17
	v_lshlrev_b32_e32 v15, 2, v15
	s_addc_u32 s49, s23, 0
	s_and_b32 s73, s4, 3
	v_lshl_or_b32 v150, s3, 6, v16
	v_lshl_or_b32 v16, v16, 6, v19
	s_lshl_b32 s3, s3, 13
	v_and_b32_e32 v15, 32, v15
	s_add_i32 m0, s65, 0x18000
	v_lshl_add_u64 v[8:9], v[8:9], 0, s[10:11]
	v_bitop3_b32 v19, v16, s3, v15 bitop3:0xde
	s_lshl_b32 s3, s73, 12
	s_waitcnt vmcnt(2)
	s_barrier
	global_load_lds_dwordx4 v[8:9], off
	v_lshl_add_u64 v[6:7], v[6:7], 0, s[10:11]
	s_add_i32 m0, s65, 0x1a000
	s_add_i32 s86, s65, 0x8000
	s_add_i32 s87, s65, 0xa000
	global_load_lds_dwordx4 v[6:7], off
	v_lshl_add_u64 v[2:3], v[2:3], 0, s[10:11]
	s_mov_b32 m0, s86
	s_add_u32 s4, s12, 0x80080
	global_load_lds_dwordx4 v[2:3], off
	v_lshl_add_u64 v[2:3], v[4:5], 0, s[10:11]
	s_mov_b32 m0, s87
	s_addc_u32 s5, s13, 0
	global_load_lds_dwordx4 v[2:3], off
	s_add_i32 m0, s65, 0x1c000
	v_lshl_add_u64 v[2:3], s[4:5], 0, v[134:135]
	global_load_lds_dwordx4 v[2:3], off
	v_lshl_add_u64 v[2:3], s[4:5], 0, v[130:131]
	s_add_i32 m0, s65, 0x1e000
	v_lshlrev_b32_e32 v18, 3, v17
	global_load_lds_dwordx4 v[2:3], off
	v_lshlrev_b32_e32 v2, 15, v0
	v_and_b32_e32 v2, 0xffff0000, v2
	v_lshl_add_u32 v2, v10, 12, v2
	v_and_b32_e32 v0, 1, v0
	v_lshl_or_b32 v0, v0, 6, v2
	v_mov_b32_e32 v138, v227
	v_lshlrev_b32_e32 v0, 15, v13
	v_and_b32_e32 v0, 0xffff0000, v0
	s_waitcnt vmcnt(6)
	v_lshl_add_u32 v0, v12, 12, v0
	v_and_b32_e32 v2, 1, v13
	v_mov_b32_e32 v151, v231
	s_cmpk_lt_u32 s2, 0x100
	v_lshl_or_b32 v0, v2, 6, v0
	v_readlane_b32 s2, v252, 21
	s_cselect_b64 s[50:51], -1, 0
	s_mov_b32 s88, 0
	v_cmp_eq_u32_e64 s[40:41], 0, v17
	v_lshl_or_b32 v152, s73, 5, v18
	v_mov_b32_e32 v139, v1
	v_mov_b32_e32 v140, v226
	v_mov_b32_e32 v141, v1
	v_mov_b32_e32 v153, v230
	v_readlane_b32 s89, v252, 4
	s_mov_b32 s4, s2
	s_barrier
	v_readlane_b32 s3, v252, 22
	s_branch .LBB0_306

; #define PG8_STAGE(bufoff, gbase, voff) do { _Pragma("unroll") for (int _i = 0; _i < 2; ++_i) \
;         __builtin_amdgcn_global_load_lds((const unsigned*)((const char*)(gbase) + (voff)[_i]), (PG8_LAS unsigned*)(lds + (bufoff) + ldsw + _i * 8192), 16, 0, 0); } while (0)
; #define PG8_LDA(dst, b, h) do { _Pragma("unroll") for (int m = 0; m < 4; ++m) _Pragma("unroll") for (int k = 0; k < 2; ++k) dst[m][k] = *(const PG8_LAS bf16x8*)(lds + PG8_SA(b, h) + aoff + m * 2048 + k * 1024); } while (0)
; #define PG8_LDB(dst, b, h) do { _Pragma("unroll") for (int n = 0; n < 2; ++n) _Pragma("unroll") for (int k = 0; k < 2; ++k) dst[n][k] = *(const PG8_LAS bf16x8*)(lds + PG8_SB(b, h) + boff + n * 2048 + k * 1024); } while (0)
; #define PG8_MMA(ai, bj, At, Bt) do { __builtin_amdgcn_s_setprio(1); _Pragma("unroll") for (int m = 0; m < 4; ++m) _Pragma("unroll") for (int n = 0; n < 2; ++n) _Pragma("unroll") for (int k = 0; k < 2; ++k) \
;         acc[ai][bj][m][n] = __builtin_amdgcn_mfma_f32_16x16x32_bf16(Bt[n][k], At[m][k], acc[ai][bj][m][n], 0, 0, 0); __builtin_amdgcn_s_setprio(0); } while (0)
; #define PG8_WAIT_V(n) asm volatile("s_waitcnt vmcnt(" #n ")" ::: "memory")
; #define PG8_WAIT_L(n) asm volatile("s_waitcnt lgkmcnt(" #n ")" ::: "memory")
; #define PG8_BAR __builtin_amdgcn_s_barrier()
; #define PG8_SCHED __builtin_amdgcn_sched_barrier(0)
; template <class Epi, class Sched, bool ALIGN_EPI = false, bool SP2 = false>
; __device__ __forceinline__ void gemm_phase(PG8_LAS unsigned char* lds, const Gemm g, const Sched& S, const Epi& E) {
;     ...
;             PG8_LDB(B0, 0, 0); PG8_LDB(B1, 0, 1); PG8_SCHED; PG8_LDA(At, 0, 0); PG8_STAGE(PG8_SA(1, 1), a1 + hstep, voffA);
;             PG8_WAIT_V(8); PG8_WAIT_L(0); PG8_BAR; PG8_MMA(0, 0, At, B0); PG8_MMA(0, 1, At, B1); PG8_BAR; PG8_SCHED;
;             PG8_LDA(At, 0, 1); PG8_STAGE(PG8_SB(0, 0), b2, voffB); PG8_STAGE(PG8_SB(0, 1), b2 + hstep, voffB); PG8_STAGE(PG8_SA(0, 0), a2, voffA);
;             PG8_WAIT_V(8); PG8_WAIT_L(0); PG8_BAR; PG8_MMA(1, 0, At, B0); PG8_MMA(1, 1, At, B1); PG8_BAR; PG8_SCHED;
.LBB0_309:
	s_add_u32 s2, s12, 0xfff80080
	s_addc_u32 s3, s13, -1
	s_add_i32 s20, 0, 0x10000
	s_cmp_eq_u32 s53, 28
	s_cselect_b32 s27, s5, s3
	s_cselect_b32 s26, s6, s2
	v_add_u32_e32 v0, s20, v151
	v_add_u32_e32 v250, s20, v249
	s_cselect_b32 s25, s7, s30
	s_cselect_b32 s24, s8, s9
	s_add_i32 s33, 0, 0x14000
	ds_read_b128 v[142:145], v0
	s_waitcnt lgkmcnt(0)
	ds_read_b128 v[146:149], v250
	ds_read_b128 v[154:157], v0 offset:2048
	ds_read_b128 v[158:161], v250 offset:2048
	v_add_u32_e32 v0, s33, v151
	v_add_u32_e32 v251, s33, v249
	ds_read_b128 v[162:165], v0
	ds_read_b128 v[166:169], v251
	ds_read_b128 v[170:173], v0 offset:2048
	ds_read_b128 v[174:177], v251 offset:2048
	s_add_i32 m0, s65, 0xc000
	ds_read_b128 v[186:189], v153
	ds_read_b128 v[190:193], v248
	ds_read_b128 v[194:197], v153 offset:2048
	ds_read_b128 v[198:201], v248 offset:2048
	ds_read_b128 v[202:205], v153 offset:4096
	ds_read_b128 v[206:209], v248 offset:4096
	ds_read_b128 v[210:213], v153 offset:6144
	ds_read_b128 v[214:217], v248 offset:6144
	global_load_lds_dwordx4 v140, s[12:13]
	s_add_i32 m0, s65, 0xe000
	s_nop 0
	global_load_lds_dwordx4 v138, s[12:13]
	s_waitcnt vmcnt(8)
	s_waitcnt lgkmcnt(0)
	s_barrier
	s_setprio 1
	s_waitcnt lgkmcnt(0)
	v_mfma_f32_16x16x32_bf16 v[126:129], v[142:145], v[186:189], v[126:129]
	v_mfma_f32_16x16x32_bf16 v[122:125], v[154:157], v[186:189], v[122:125]
	v_mfma_f32_16x16x32_bf16 v[110:113], v[142:145], v[194:197], v[110:113]
	v_mfma_f32_16x16x32_bf16 v[106:109], v[154:157], v[194:197], v[106:109]
	v_mfma_f32_16x16x32_bf16 v[94:97], v[142:145], v[202:205], v[94:97]
	v_mfma_f32_16x16x32_bf16 v[90:93], v[154:157], v[202:205], v[90:93]
	v_mfma_f32_16x16x32_bf16 v[78:81], v[142:145], v[210:213], v[78:81]
	v_mfma_f32_16x16x32_bf16 v[74:77], v[154:157], v[210:213], v[74:77]
	v_mfma_f32_16x16x32_bf16 v[126:129], v[146:149], v[190:193], v[126:129]
	v_mfma_f32_16x16x32_bf16 v[122:125], v[158:161], v[190:193], v[122:125]
	v_mfma_f32_16x16x32_bf16 v[110:113], v[146:149], v[198:201], v[110:113]
	v_mfma_f32_16x16x32_bf16 v[106:109], v[158:161], v[198:201], v[106:109]
	v_mfma_f32_16x16x32_bf16 v[94:97], v[146:149], v[206:209], v[94:97]
	v_mfma_f32_16x16x32_bf16 v[90:93], v[158:161], v[206:209], v[90:93]
	v_mfma_f32_16x16x32_bf16 v[78:81], v[146:149], v[214:217], v[78:81]
	v_mfma_f32_16x16x32_bf16 v[74:77], v[158:161], v[214:217], v[74:77]
	s_setprio 0
	s_setprio 1
	v_mfma_f32_16x16x32_bf16 v[118:121], v[162:165], v[186:189], v[118:121]
	v_mfma_f32_16x16x32_bf16 v[114:117], v[170:173], v[186:189], v[114:117]
	v_mfma_f32_16x16x32_bf16 v[102:105], v[162:165], v[194:197], v[102:105]
	v_mfma_f32_16x16x32_bf16 v[98:101], v[170:173], v[194:197], v[98:101]
	v_mfma_f32_16x16x32_bf16 v[86:89], v[162:165], v[202:205], v[86:89]
	v_mfma_f32_16x16x32_bf16 v[82:85], v[170:173], v[202:205], v[82:85]
	v_mfma_f32_16x16x32_bf16 v[70:73], v[162:165], v[210:213], v[70:73]
	v_mfma_f32_16x16x32_bf16 v[66:69], v[170:173], v[210:213], v[66:69]
	v_mfma_f32_16x16x32_bf16 v[118:121], v[166:169], v[190:193], v[118:121]
	v_mfma_f32_16x16x32_bf16 v[114:117], v[174:177], v[190:193], v[114:117]
	v_mfma_f32_16x16x32_bf16 v[102:105], v[166:169], v[198:201], v[102:105]
	v_mfma_f32_16x16x32_bf16 v[98:101], v[174:177], v[198:201], v[98:101]
	v_mfma_f32_16x16x32_bf16 v[86:89], v[166:169], v[206:209], v[86:89]
	v_mfma_f32_16x16x32_bf16 v[82:85], v[174:177], v[206:209], v[82:85]
	v_mfma_f32_16x16x32_bf16 v[70:73], v[166:169], v[214:217], v[70:73]
	v_mfma_f32_16x16x32_bf16 v[66:69], v[174:177], v[214:217], v[66:69]
	s_setprio 0
	s_barrier
	s_add_i32 s2, s20, s64
	s_mov_b32 m0, s2
	ds_read_b128 v[186:189], v153 offset:16384
	ds_read_b128 v[190:193], v248 offset:16384
	ds_read_b128 v[194:197], v153 offset:18432
	ds_read_b128 v[198:201], v248 offset:18432
	ds_read_b128 v[202:205], v153 offset:20480
	ds_read_b128 v[206:209], v248 offset:20480
	ds_read_b128 v[210:213], v153 offset:22528
	ds_read_b128 v[214:217], v248 offset:22528
	global_load_lds_dwordx4 v134, s[24:25]
	s_add_i32 m0, s2, 0x2000
	s_add_u32 s2, s24, 0x80000
	s_addc_u32 s3, s25, 0
	s_add_i32 s20, s33, s64
	global_load_lds_dwordx4 v130, s[24:25]
	s_mov_b32 m0, s20
	s_nop 0
	global_load_lds_dwordx4 v134, s[2:3]
	s_add_i32 m0, s20, 0x2000
	s_nop 0
	global_load_lds_dwordx4 v130, s[2:3]
	s_mov_b32 m0, s65
	s_nop 0
	global_load_lds_dwordx4 v136, s[26:27]
	s_mov_b32 m0, s66
	s_nop 0
	global_load_lds_dwordx4 v132, s[26:27]
	s_waitcnt vmcnt(8)
	s_waitcnt lgkmcnt(0)
	s_barrier
	s_setprio 1
	s_waitcnt lgkmcnt(0)
	v_mfma_f32_16x16x32_bf16 v[62:65], v[142:145], v[186:189], v[62:65]
	v_mfma_f32_16x16x32_bf16 v[58:61], v[154:157], v[186:189], v[58:61]
	v_mfma_f32_16x16x32_bf16 v[46:49], v[142:145], v[194:197], v[46:49]
	v_mfma_f32_16x16x32_bf16 v[42:45], v[154:157], v[194:197], v[42:45]
	v_mfma_f32_16x16x32_bf16 v[30:33], v[142:145], v[202:205], v[30:33]
	v_mfma_f32_16x16x32_bf16 v[26:29], v[154:157], v[202:205], v[26:29]
	v_mfma_f32_16x16x32_bf16 v[14:17], v[142:145], v[210:213], v[14:17]
	v_mfma_f32_16x16x32_bf16 v[10:13], v[154:157], v[210:213], v[10:13]
	v_mfma_f32_16x16x32_bf16 v[62:65], v[146:149], v[190:193], v[62:65]
	v_mfma_f32_16x16x32_bf16 v[58:61], v[158:161], v[190:193], v[58:61]
	v_mfma_f32_16x16x32_bf16 v[46:49], v[146:149], v[198:201], v[46:49]
	v_mfma_f32_16x16x32_bf16 v[42:45], v[158:161], v[198:201], v[42:45]
	v_mfma_f32_16x16x32_bf16 v[30:33], v[146:149], v[206:209], v[30:33]
	v_mfma_f32_16x16x32_bf16 v[26:29], v[158:161], v[206:209], v[26:29]
	v_mfma_f32_16x16x32_bf16 v[14:17], v[146:149], v[214:217], v[14:17]
	v_mfma_f32_16x16x32_bf16 v[10:13], v[158:161], v[214:217], v[10:13]
	s_setprio 0
	s_setprio 1
	v_mfma_f32_16x16x32_bf16 v[54:57], v[162:165], v[186:189], v[54:57]
	v_mfma_f32_16x16x32_bf16 v[50:53], v[170:173], v[186:189], v[50:53]
	v_mfma_f32_16x16x32_bf16 v[38:41], v[162:165], v[194:197], v[38:41]
	v_mfma_f32_16x16x32_bf16 v[34:37], v[170:173], v[194:197], v[34:37]
	v_mfma_f32_16x16x32_bf16 v[22:25], v[162:165], v[202:205], v[22:25]
	v_mfma_f32_16x16x32_bf16 v[18:21], v[170:173], v[202:205], v[18:21]
	v_mfma_f32_16x16x32_bf16 v[6:9], v[162:165], v[210:213], v[6:9]
	v_mfma_f32_16x16x32_bf16 v[2:5], v[170:173], v[210:213], v[2:5]
	v_mfma_f32_16x16x32_bf16 v[54:57], v[166:169], v[190:193], v[54:57]
	v_mfma_f32_16x16x32_bf16 v[50:53], v[174:177], v[190:193], v[50:53]
	v_mfma_f32_16x16x32_bf16 v[38:41], v[166:169], v[198:201], v[38:41]
	v_mfma_f32_16x16x32_bf16 v[34:37], v[174:177], v[198:201], v[34:37]
	v_mfma_f32_16x16x32_bf16 v[22:25], v[166:169], v[206:209], v[22:25]
	v_mfma_f32_16x16x32_bf16 v[18:21], v[174:177], v[206:209], v[18:21]
	v_mfma_f32_16x16x32_bf16 v[6:9], v[166:169], v[214:217], v[6:9]
	v_mfma_f32_16x16x32_bf16 v[2:5], v[174:177], v[214:217], v[2:5]
	s_setprio 0
	s_barrier
; #define PG8_STAGE(bufoff, gbase, voff) do { _Pragma("unroll") for (int _i = 0; _i < 2; ++_i) \
;         __builtin_amdgcn_global_load_lds((const unsigned*)((const char*)(gbase) + (voff)[_i]), (PG8_LAS unsigned*)(lds + (bufoff) + ldsw + _i * 8192), 16, 0, 0); } while (0)
; #define PG8_LDA(dst, b, h) do { _Pragma("unroll") for (int m = 0; m < 4; ++m) _Pragma("unroll") for (int k = 0; k < 2; ++k) dst[m][k] = *(const PG8_LAS bf16x8*)(lds + PG8_SA(b, h) + aoff + m * 2048 + k * 1024); } while (0)
; #define PG8_LDB(dst, b, h) do { _Pragma("unroll") for (int n = 0; n < 2; ++n) _Pragma("unroll") for (int k = 0; k < 2; ++k) dst[n][k] = *(const PG8_LAS bf16x8*)(lds + PG8_SB(b, h) + boff + n * 2048 + k * 1024); } while (0)
; #define PG8_MMA(ai, bj, At, Bt) do { __builtin_amdgcn_s_setprio(1); _Pragma("unroll") for (int m = 0; m < 4; ++m) _Pragma("unroll") for (int n = 0; n < 2; ++n) _Pragma("unroll") for (int k = 0; k < 2; ++k) \
;         acc[ai][bj][m][n] = __builtin_amdgcn_mfma_f32_16x16x32_bf16(Bt[n][k], At[m][k], acc[ai][bj][m][n], 0, 0, 0); __builtin_amdgcn_s_setprio(0); } while (0)
; #define PG8_WAIT_V(n) asm volatile("s_waitcnt vmcnt(" #n ")" ::: "memory")
; #define PG8_WAIT_L(n) asm volatile("s_waitcnt lgkmcnt(" #n ")" ::: "memory")
; #define PG8_BAR __builtin_amdgcn_s_barrier()
; #define PG8_SCHED __builtin_amdgcn_sched_barrier(0)
; template <class Epi, class Sched, bool ALIGN_EPI = false, bool SP2 = false>
; __device__ __forceinline__ void gemm_phase(PG8_LAS unsigned char* lds, const Gemm g, const Sched& S, const Epi& E) {
;     ...
;         for (int t = 0; t < nt; t += 2) {
;     ...
;             PG8_LDB(B0, 1, 0); PG8_LDB(B1, 1, 1); PG8_SCHED; PG8_LDA(At, 1, 0); PG8_STAGE(PG8_SA(0, 1), a2 + hstep, voffA);
;             PG8_WAIT_V(8); PG8_WAIT_L(0); PG8_BAR; PG8_MMA(0, 0, At, B0); PG8_MMA(0, 1, At, B1); PG8_BAR; PG8_SCHED;
;             PG8_LDA(At, 1, 1); PG8_STAGE(PG8_SB(1, 0), b3, voffB); PG8_STAGE(PG8_SB(1, 1), b3 + hstep, voffB); PG8_STAGE(PG8_SA(1, 0), a3, voffA);
;             PG8_WAIT_V(8); PG8_WAIT_L(0); PG8_BAR; PG8_MMA(1, 0, At, B0); PG8_MMA(1, 1, At, B1); PG8_BAR; PG8_SCHED;
	s_add_i32 s20, 0, 0x18000
	v_add_u32_e32 v0, s20, v151
	v_add_u32_e32 v250, s20, v249
	s_add_i32 s33, 0, 0x1c000
	ds_read_b128 v[142:145], v0
	ds_read_b128 v[146:149], v250
	ds_read_b128 v[154:157], v0 offset:2048
	ds_read_b128 v[158:161], v250 offset:2048
	v_add_u32_e32 v0, s33, v151
	v_add_u32_e32 v251, s33, v249
	ds_read_b128 v[162:165], v0
	ds_read_b128 v[166:169], v251
	ds_read_b128 v[170:173], v0 offset:2048
	ds_read_b128 v[174:177], v251 offset:2048
	s_add_u32 s2, s26, 0x80000
	s_addc_u32 s3, s27, 0
	s_mov_b32 m0, s67
	ds_read_b128 v[186:189], v153 offset:32768
	ds_read_b128 v[190:193], v248 offset:32768
	ds_read_b128 v[194:197], v153 offset:34816
	ds_read_b128 v[198:201], v248 offset:34816
	ds_read_b128 v[202:205], v153 offset:36864
	ds_read_b128 v[206:209], v248 offset:36864
	ds_read_b128 v[210:213], v153 offset:38912
	ds_read_b128 v[214:217], v248 offset:38912
	global_load_lds_dwordx4 v136, s[2:3]
	s_mov_b32 m0, s72
	s_nop 0
	global_load_lds_dwordx4 v132, s[2:3]
	s_waitcnt vmcnt(8)
	s_waitcnt lgkmcnt(0)
	s_barrier
	s_setprio 1
	s_waitcnt lgkmcnt(0)
	v_mfma_f32_16x16x32_bf16 v[126:129], v[142:145], v[186:189], v[126:129]
	v_mfma_f32_16x16x32_bf16 v[122:125], v[154:157], v[186:189], v[122:125]
	v_mfma_f32_16x16x32_bf16 v[110:113], v[142:145], v[194:197], v[110:113]
	v_mfma_f32_16x16x32_bf16 v[106:109], v[154:157], v[194:197], v[106:109]
	v_mfma_f32_16x16x32_bf16 v[94:97], v[142:145], v[202:205], v[94:97]
	v_mfma_f32_16x16x32_bf16 v[90:93], v[154:157], v[202:205], v[90:93]
	v_mfma_f32_16x16x32_bf16 v[78:81], v[142:145], v[210:213], v[78:81]
	v_mfma_f32_16x16x32_bf16 v[74:77], v[154:157], v[210:213], v[74:77]
	v_mfma_f32_16x16x32_bf16 v[126:129], v[146:149], v[190:193], v[126:129]
	v_mfma_f32_16x16x32_bf16 v[122:125], v[158:161], v[190:193], v[122:125]
	v_mfma_f32_16x16x32_bf16 v[110:113], v[146:149], v[198:201], v[110:113]
	v_mfma_f32_16x16x32_bf16 v[106:109], v[158:161], v[198:201], v[106:109]
	v_mfma_f32_16x16x32_bf16 v[94:97], v[146:149], v[206:209], v[94:97]
	v_mfma_f32_16x16x32_bf16 v[90:93], v[158:161], v[206:209], v[90:93]
	v_mfma_f32_16x16x32_bf16 v[78:81], v[146:149], v[214:217], v[78:81]
	v_mfma_f32_16x16x32_bf16 v[74:77], v[158:161], v[214:217], v[74:77]
	s_setprio 0
	s_setprio 1
	v_mfma_f32_16x16x32_bf16 v[118:121], v[162:165], v[186:189], v[118:121]
	v_mfma_f32_16x16x32_bf16 v[114:117], v[170:173], v[186:189], v[114:117]
	v_mfma_f32_16x16x32_bf16 v[102:105], v[162:165], v[194:197], v[102:105]
	v_mfma_f32_16x16x32_bf16 v[98:101], v[170:173], v[194:197], v[98:101]
	v_mfma_f32_16x16x32_bf16 v[86:89], v[162:165], v[202:205], v[86:89]
	v_mfma_f32_16x16x32_bf16 v[82:85], v[170:173], v[202:205], v[82:85]
	v_mfma_f32_16x16x32_bf16 v[70:73], v[162:165], v[210:213], v[70:73]
	v_mfma_f32_16x16x32_bf16 v[66:69], v[170:173], v[210:213], v[66:69]
	v_mfma_f32_16x16x32_bf16 v[118:121], v[166:169], v[190:193], v[118:121]
	v_mfma_f32_16x16x32_bf16 v[114:117], v[174:177], v[190:193], v[114:117]
	v_mfma_f32_16x16x32_bf16 v[102:105], v[166:169], v[198:201], v[102:105]
	v_mfma_f32_16x16x32_bf16 v[98:101], v[174:177], v[198:201], v[98:101]
	v_mfma_f32_16x16x32_bf16 v[86:89], v[166:169], v[206:209], v[86:89]
	v_mfma_f32_16x16x32_bf16 v[82:85], v[174:177], v[206:209], v[82:85]
	v_mfma_f32_16x16x32_bf16 v[70:73], v[166:169], v[214:217], v[70:73]
	v_mfma_f32_16x16x32_bf16 v[66:69], v[174:177], v[214:217], v[66:69]
	s_setprio 0
	s_barrier
	s_add_i32 s2, s20, s64
	s_add_i32 m0, s2, 0xffffff80
	ds_read_b128 v[186:189], v153 offset:49152
	ds_read_b128 v[190:193], v248 offset:49152
	ds_read_b128 v[194:197], v153 offset:51200
	ds_read_b128 v[198:201], v248 offset:51200
	ds_read_b128 v[202:205], v153 offset:53248
	ds_read_b128 v[206:209], v248 offset:53248
	ds_read_b128 v[210:213], v153 offset:55296
	ds_read_b128 v[214:217], v248 offset:55296
	global_load_lds_dwordx4 v134, s[24:25] offset:128
	s_add_i32 m0, s2, 0x1f80
	s_add_u32 s2, s24, 0x80080
	s_addc_u32 s3, s25, 0
	s_add_i32 s20, s33, s64
	global_load_lds_dwordx4 v130, s[24:25] offset:128
	s_mov_b32 m0, s20
	s_nop 0
	global_load_lds_dwordx4 v134, s[2:3]
	s_add_i32 m0, s20, 0x2000
	s_nop 0
	global_load_lds_dwordx4 v130, s[2:3]
	s_add_i32 m0, s86, 0xffffff80
	s_nop 0
	global_load_lds_dwordx4 v136, s[26:27] offset:128
	s_add_i32 m0, s87, 0xffffff80
	s_nop 0
	global_load_lds_dwordx4 v132, s[26:27] offset:128
	s_waitcnt vmcnt(8)
	s_waitcnt lgkmcnt(0)
	s_barrier
	s_setprio 1
	s_waitcnt lgkmcnt(0)
	v_mfma_f32_16x16x32_bf16 v[62:65], v[142:145], v[186:189], v[62:65]
	v_mfma_f32_16x16x32_bf16 v[58:61], v[154:157], v[186:189], v[58:61]
	v_mfma_f32_16x16x32_bf16 v[46:49], v[142:145], v[194:197], v[46:49]
	v_mfma_f32_16x16x32_bf16 v[42:45], v[154:157], v[194:197], v[42:45]
	v_mfma_f32_16x16x32_bf16 v[30:33], v[142:145], v[202:205], v[30:33]
	v_mfma_f32_16x16x32_bf16 v[26:29], v[154:157], v[202:205], v[26:29]
	v_mfma_f32_16x16x32_bf16 v[14:17], v[142:145], v[210:213], v[14:17]
	v_mfma_f32_16x16x32_bf16 v[10:13], v[154:157], v[210:213], v[10:13]
	v_mfma_f32_16x16x32_bf16 v[62:65], v[146:149], v[190:193], v[62:65]
	v_mfma_f32_16x16x32_bf16 v[58:61], v[158:161], v[190:193], v[58:61]
	v_mfma_f32_16x16x32_bf16 v[46:49], v[146:149], v[198:201], v[46:49]
	v_mfma_f32_16x16x32_bf16 v[42:45], v[158:161], v[198:201], v[42:45]
	v_mfma_f32_16x16x32_bf16 v[30:33], v[146:149], v[206:209], v[30:33]
	v_mfma_f32_16x16x32_bf16 v[26:29], v[158:161], v[206:209], v[26:29]
	v_mfma_f32_16x16x32_bf16 v[14:17], v[146:149], v[214:217], v[14:17]
	v_mfma_f32_16x16x32_bf16 v[10:13], v[158:161], v[214:217], v[10:13]
	s_setprio 0
	s_setprio 1
	v_mfma_f32_16x16x32_bf16 v[54:57], v[162:165], v[186:189], v[54:57]
	v_mfma_f32_16x16x32_bf16 v[50:53], v[170:173], v[186:189], v[50:53]
	v_mfma_f32_16x16x32_bf16 v[38:41], v[162:165], v[194:197], v[38:41]
	v_mfma_f32_16x16x32_bf16 v[34:37], v[170:173], v[194:197], v[34:37]
	v_mfma_f32_16x16x32_bf16 v[22:25], v[162:165], v[202:205], v[22:25]
	v_mfma_f32_16x16x32_bf16 v[18:21], v[170:173], v[202:205], v[18:21]
	v_mfma_f32_16x16x32_bf16 v[6:9], v[162:165], v[210:213], v[6:9]
	v_mfma_f32_16x16x32_bf16 v[2:5], v[170:173], v[210:213], v[2:5]
	v_mfma_f32_16x16x32_bf16 v[54:57], v[166:169], v[190:193], v[54:57]
	v_mfma_f32_16x16x32_bf16 v[50:53], v[174:177], v[190:193], v[50:53]
	v_mfma_f32_16x16x32_bf16 v[38:41], v[166:169], v[198:201], v[38:41]
	v_mfma_f32_16x16x32_bf16 v[34:37], v[174:177], v[198:201], v[34:37]
	v_mfma_f32_16x16x32_bf16 v[22:25], v[166:169], v[206:209], v[22:25]
	v_mfma_f32_16x16x32_bf16 v[18:21], v[174:177], v[206:209], v[18:21]
	v_mfma_f32_16x16x32_bf16 v[6:9], v[166:169], v[214:217], v[6:9]
	v_mfma_f32_16x16x32_bf16 v[2:5], v[174:177], v[214:217], v[2:5]
	s_setprio 0
	s_barrier
	s_add_i32 s53, s53, 2
	s_add_u32 s9, s9, 0x100
	s_addc_u32 s30, s30, 0
	s_add_u32 s12, s12, 0x100
	s_addc_u32 s13, s13, 0
	s_cmp_gt_u32 s53, 29
	s_cbranch_scc0 .LBB0_309
	s_and_b64 vcc, exec, s[50:51]
	s_cbranch_vccz .LBB0_312
	s_barrier

; #define PG8_STAGE(bufoff, gbase, voff) do { _Pragma("unroll") for (int _i = 0; _i < 2; ++_i) \
;         __builtin_amdgcn_global_load_lds((const unsigned*)((const char*)(gbase) + (voff)[_i]), (PG8_LAS unsigned*)(lds + (bufoff) + ldsw + _i * 8192), 16, 0, 0); } while (0)
; #define PG8_WAIT_V(n) asm volatile("s_waitcnt vmcnt(" #n ")" ::: "memory")
; #define PG8_BAR __builtin_amdgcn_s_barrier()
; template <class Epi, class Sched, bool ALIGN_EPI = false, bool SP2 = false>
; __device__ __forceinline__ void gemm_phase(PG8_LAS unsigned char* lds, const Gemm g, const Sched& S, const Epi& E) {
;     int tid_ = threadIdx.x; asm volatile("" : "+v"(tid_));
;     const int tid = tid_, wid = __builtin_amdgcn_readfirstlane(tid >> 6), lane = tid & 63, wr = wid >> 2, wc = wid & 3, fr = lane & 15, fq = lane >> 4;
;     const int K = g.K, nt = K / BK;
;     unsigned voffA[2], voffB[2];
; #pragma unroll
;     for (int i = 0; i < 2; ++i) { int R, C; stage_rc(tid * 16 + i * 8192, R, C); const int Rb = Epi::PERM ? ((R & ~31) + perm32(R & 31)) : R;
;         voffA[i] = (unsigned)(R * K + C) * 2u; voffB[i] = (unsigned)(Rb * K + C) * 2u; }
;     const size_t kstep = (size_t)(BK * 2);
;     const size_t hstep = (size_t)HALF * K * 2;
;     const size_t tstep = 2 * hstep;
;     const unsigned ldsw = (unsigned)wid * 1024u;
;     const int aoff = lds_byte(wr * 64 + fr, fq * 8), boff = lds_byte(wc * 32 + fr, fq * 8);
;     ...
;     const char* cA = (const char*)g.A + (size_t)(cur.pm & g.pm_mask) * tstep; const char* cB = (const char*)g.Bt + (size_t)cur.pn * tstep;
;     S.a_ready(cur);
;     if constexpr (SP2) {
;         PG8_STAGE(PG8_SB(0, 0), cB, voffB); PG8_STAGE(PG8_SB(0, 1), cB + hstep, voffB); PG8_STAGE(PG8_SA(0, 0), cA, voffA); PG8_STAGE(PG8_SA(0, 1), cA + hstep, voffA);
;         if (wr == 1) PG8_BAR;
;         PG8_WAIT_V(2); PG8_BAR;
.LBB0_337:
	s_andn2_b64 vcc, exec, s[12:13]
	s_cbranch_vccnz .LBB0_750
	v_readlane_b32 s2, v252, 5
	v_mov_b32_e32 v0, v178
	v_readlane_b32 s3, v252, 6
	s_andn2_b64 vcc, exec, s[2:3]
	v_readfirstlane_b32 s2, v0
	s_cbranch_vccnz .LBB0_750
	v_lshlrev_b32_e32 v2, 4, v0
	v_add_u32_e32 v3, 0x2000, v2
	v_ashrrev_i32_e32 v4, 31, v3
	v_lshrrev_b32_e32 v4, 22, v4
	v_add_u32_e32 v4, v3, v4
	v_ashrrev_i32_e32 v10, 10, v4
	v_mul_i32_i24_e32 v4, 0x400, v10
	v_sub_u32_e32 v3, v3, v4
	v_lshrrev_b32_e32 v4, 4, v3
	v_bitop3_b32 v3, v4, v3, 32 bitop3:0x6c
	v_readlane_b32 s4, v252, 56
	v_ashrrev_i32_e32 v4, 31, v3
	v_readlane_b32 s5, v252, 57
	v_lshrrev_b32_e32 v4, 26, v4
	s_ashr_i32 s5, s4, 31
	v_add_u32_e32 v4, v3, v4
	v_lshlrev_b32_e32 v5, 3, v10
	s_lshl_b64 s[4:5], s[4:5], 25
	v_ashrrev_i32_e32 v11, 6, v4
	v_and_b32_e32 v5, -16, v5
	s_add_u32 s30, s22, s4
	v_add_u32_e32 v5, v11, v5
	s_addc_u32 s56, s23, s5
	v_and_b32_e32 v6, 3, v11
	s_mov_b32 s5, 0xfffe0
	v_lshrrev_b32_e32 v7, 2, v5
	v_lshlrev_b32_e32 v8, 1, v5
	v_and_b32_e32 v4, 0xc0, v4
	v_and_or_b32 v6, v5, s5, v6
	v_and_b32_e32 v7, 4, v7
	v_and_b32_e32 v8, 24, v8
	v_sub_u32_e32 v3, v3, v4
	v_or3_b32 v6, v6, v7, v8
	v_lshlrev_b32_e32 v7, 5, v10
	v_ashrrev_i16_sdwa v3, v179, sext(v3) dst_sel:DWORD dst_unused:UNUSED_PAD src0_sel:DWORD src1_sel:BYTE_0
	v_and_b32_e32 v7, 32, v7
	v_bfe_i32 v12, v3, 0, 16
	v_add_lshl_u32 v3, v7, v12, 1
	v_and_b32_e32 v232, 63, v178
	v_lshrrev_b32_e32 v233, 6, v178
	v_lshrrev_b32_e32 v234, 3, v232
	v_and_b32_e32 v235, 7, v232
	v_bfe_u32 v246, v234, 1, 2
	v_and_b32_e32 v226, 1, v233
	v_lshl_or_b32 v246, v226, 2, v246
	v_xor_b32_e32 v235, v235, v246
	v_lshlrev_b32_e32 v235, 4, v235
	v_lshl_add_u32 v227, v233, 3, v234
	v_lshl_add_u32 v226, v227, 12, v235
	v_add_u32_e32 v227, 0x40000, v226
	v_and_b32_e32 v228, 1, v233
	v_lshrrev_b32_e32 v229, 2, v234
	v_lshl_add_u32 v228, v228, 1, v229
	v_bfe_u32 v229, v233, 1, 1
	v_and_b32_e32 v246, 3, v234
	v_lshl_or_b32 v229, v229, 2, v246
	v_lshl_add_u32 v228, v228, 3, v229
	v_lshrrev_b32_e32 v229, 2, v233
	v_lshl_add_u32 v228, v229, 5, v228
	v_lshl_add_u32 v228, v228, 12, v235
	v_add_u32_e32 v229, 0x40000, v228
	v_and_b32_e32 v246, 15, v232
	v_lshrrev_b32_e32 v234, 4, v232
	v_bfe_u32 v230, v246, 1, 2
	v_lshrrev_b32_e32 v231, 3, v246
	v_lshl_or_b32 v230, v231, 2, v230
	v_xor_b32_e32 v230, v230, v234
	v_lshlrev_b32_e32 v230, 4, v230
	v_lshl_add_u32 v230, v231, 10, v230
	v_and_b32_e32 v231, 7, v246
	v_lshl_add_u32 v230, v231, 7, v230
	v_and_b32_e32 v231, 3, v233
	v_lshl_add_u32 v231, v231, 12, v230
	v_lshrrev_b32_e32 v246, 2, v233
	v_lshl_add_u32 v230, v246, 13, v230
	v_xor_b32_e32 v248, 64, v230
	v_xor_b32_e32 v249, 64, v231
	v_mov_b32_e32 v146, v229
	s_waitcnt lgkmcnt(0)
	v_mov_b32_e32 v148, v227
	v_bfe_i32 v3, v0, 27, 1
	v_lshrrev_b32_e32 v3, 22, v3
	v_add_u32_e32 v3, v2, v3
	v_and_b32_e32 v3, 0xfffffc00, v3
	v_sub_u32_e32 v2, v2, v3
	v_lshrrev_b32_e32 v3, 4, v2
	v_ashrrev_i32_e32 v4, 31, v0
	v_bitop3_b32 v2, v3, v2, 32 bitop3:0x6c
	v_lshrrev_b32_e32 v4, 26, v4
	v_ashrrev_i32_e32 v3, 31, v2
	v_add_u32_e32 v4, v0, v4
	v_lshrrev_b32_e32 v3, 26, v3
	v_ashrrev_i32_e32 v14, 6, v4
	v_add_u32_e32 v3, v2, v3
	v_lshlrev_b32_e32 v4, 3, v14
	v_ashrrev_i32_e32 v13, 6, v3
	v_and_b32_e32 v4, -16, v4
	v_add_u32_e32 v4, v13, v4
	v_and_b32_e32 v5, 3, v13
	v_lshrrev_b32_e32 v6, 2, v4
	v_lshlrev_b32_e32 v7, 1, v4
	v_and_b32_e32 v3, 0xc0, v3
	s_ashr_i32 s3, s2, 6
	v_and_or_b32 v5, v4, s5, v5
	v_and_b32_e32 v6, 4, v6
	v_and_b32_e32 v7, 24, v7
	v_sub_u32_e32 v2, v2, v3
	s_ashr_i32 s4, s2, 8
	s_lshl_b32 s57, s3, 10
	v_or3_b32 v5, v5, v6, v7
	v_lshlrev_b32_e32 v6, 5, v14
	v_ashrrev_i16_sdwa v2, v179, sext(v2) dst_sel:DWORD dst_unused:UNUSED_PAD src0_sel:DWORD src1_sel:BYTE_0
	v_readlane_b32 s6, v252, 15
	v_and_b32_e32 v6, 32, v6
	v_bfe_i32 v15, v2, 0, 16
	v_readlane_b32 s7, v252, 16
	s_add_u32 s12, s30, s6
	v_add_lshl_u32 v2, v6, v15, 1
	s_addc_u32 s13, s56, s7
	s_add_i32 s58, s57, 0
	v_mov_b32_e32 v150, v228
	s_add_i32 m0, s58, 0x10000
	v_mov_b32_e32 v152, v226
	global_load_lds_dwordx4 v150, s[12:13]
	s_add_i32 m0, s58, 0x12000
	s_add_u32 s6, s12, 0x80000
	global_load_lds_dwordx4 v146, s[12:13]
	s_addc_u32 s7, s13, 0
	s_add_i32 m0, s58, 0x14000
	v_mov_b32_e32 v151, v1
	global_load_lds_dwordx4 v150, s[6:7]
	s_add_i32 m0, s58, 0x16000
	v_mov_b32_e32 v147, v1
	global_load_lds_dwordx4 v146, s[6:7]
	v_readlane_b32 s6, v252, 27
	v_readlane_b32 s7, v252, 28
	s_add_u32 s24, s70, s6
	s_addc_u32 s25, s71, s7
	s_add_i32 s59, s58, 0x2000
	s_mov_b32 m0, s58
	s_add_u32 s6, s24, 0x80000
	global_load_lds_dwordx4 v152, s[24:25]
	s_mov_b32 m0, s59
	s_addc_u32 s7, s25, 0
	s_add_i32 s60, s58, 0x4000
	global_load_lds_dwordx4 v148, s[24:25]
	s_mov_b32 m0, s60
	s_add_i32 s61, s58, 0x6000
	global_load_lds_dwordx4 v152, s[6:7]
	s_mov_b32 m0, s61
	v_mov_b32_e32 v153, v1
	global_load_lds_dwordx4 v148, s[6:7]
	v_mov_b32_e32 v149, v1
	s_cmp_eq_u32 s4, 1
	v_lshl_add_u64 v[8:9], s[12:13], 0, v[150:151]
	v_lshl_add_u64 v[6:7], s[12:13], 0, v[146:147]
	v_lshl_add_u64 v[2:3], s[24:25], 0, v[152:153]
	s_cselect_b64 s[16:17], -1, 0
	s_cmp_lg_u32 s4, 1
	v_lshl_add_u64 v[4:5], s[24:25], 0, v[148:149]
	s_cbranch_scc1 .LBB0_341
	s_barrier
; #define PG8_STAGE(bufoff, gbase, voff) do { _Pragma("unroll") for (int _i = 0; _i < 2; ++_i) \
;         __builtin_amdgcn_global_load_lds((const unsigned*)((const char*)(gbase) + (voff)[_i]), (PG8_LAS unsigned*)(lds + (bufoff) + ldsw + _i * 8192), 16, 0, 0); } while (0)
; #define PG8_WAIT_V(n) asm volatile("s_waitcnt vmcnt(" #n ")" ::: "memory")
; #define PG8_BAR __builtin_amdgcn_s_barrier()
; template <class Epi, class Sched, bool ALIGN_EPI = false, bool SP2 = false>
; __device__ __forceinline__ void gemm_phase(PG8_LAS unsigned char* lds, const Gemm g, const Sched& S, const Epi& E) {
;     ...
;     const unsigned ldsw = (unsigned)wid * 1024u;
;     const int aoff = lds_byte(wr * 64 + fr, fq * 8), boff = lds_byte(wc * 32 + fr, fq * 8);
;     ...
;         PG8_STAGE(PG8_SB(1, 0), cB + kstep, voffB); PG8_STAGE(PG8_SA(1, 0), cA + kstep, voffA); PG8_STAGE(PG8_SB(1, 1), cB + hstep + kstep, voffB);
;         PG8_WAIT_V(6); PG8_BAR;
.LBB0_341:
	v_lshrrev_b32_e32 v17, 1, v0
	v_and_b32_e32 v17, 24, v17
	v_and_b32_e32 v16, 15, v0
	v_lshlrev_b32_e32 v18, 1, v17
	v_lshlrev_b32_e32 v0, 2, v0
	s_and_b32 s6, s3, 3
	v_lshl_or_b32 v168, s4, 6, v16
	v_lshl_or_b32 v16, v16, 6, v18
	s_lshl_b32 s4, s4, 13
	v_and_b32_e32 v0, 32, v0
	s_add_i32 m0, s58, 0x18000
	v_lshl_add_u64 v[8:9], v[8:9], 0, s[10:11]
	v_bitop3_b32 v18, v16, s4, v0 bitop3:0xde
	s_lshl_b32 s7, s6, 5
	s_lshl_b32 s4, s6, 12
	s_waitcnt vmcnt(2)
	s_barrier
	global_load_lds_dwordx4 v[8:9], off
	v_lshl_add_u64 v[6:7], v[6:7], 0, s[10:11]
	s_add_i32 m0, s58, 0x1a000
	s_add_i32 s64, s58, 0x8000
	s_add_i32 s65, s58, 0xa000
	v_mov_b32_e32 v169, v231
	global_load_lds_dwordx4 v[6:7], off
	v_lshl_add_u64 v[2:3], v[2:3], 0, s[10:11]
	s_mov_b32 m0, s64
	s_add_u32 s4, s12, 0x80080
	global_load_lds_dwordx4 v[2:3], off
	v_lshl_add_u64 v[2:3], v[4:5], 0, s[10:11]
	s_mov_b32 m0, s65
	s_addc_u32 s5, s13, 0
	global_load_lds_dwordx4 v[2:3], off
	s_add_i32 m0, s58, 0x1c000
	v_lshl_add_u64 v[2:3], s[4:5], 0, v[150:151]
	global_load_lds_dwordx4 v[2:3], off
	v_lshl_add_u64 v[2:3], s[4:5], 0, v[146:147]
	s_add_i32 m0, s58, 0x1e000
	s_cmpk_lt_u32 s2, 0x100
	global_load_lds_dwordx4 v[2:3], off
	v_and_or_b32 v2, s7, 32, v17
	v_lshlrev_b32_e32 v0, 2, v2
	v_lshl_add_u64 v[4:5], s[22:23], 0, v[0:1]
	v_lshlrev_b32_e32 v0, 15, v10
	v_and_b32_e32 v0, 0xffff0000, v0
	s_cselect_b64 s[26:27], -1, 0
	s_cmp_gt_u32 s6, 1
	v_lshl_add_u32 v0, v11, 12, v0
	v_and_b32_e32 v3, 1, v10
	s_cselect_b64 s[44:45], -1, 0
	s_bfe_u32 s66, s3, 0x10001
	s_mov_b64 s[2:3], 0x90e4000
	v_lshl_or_b32 v0, v3, 6, v0
	v_lshl_add_u64 v[154:155], v[4:5], 0, s[2:3]
	s_mov_b64 s[2:3], 0x91e4000
	v_mov_b32_e32 v158, v227
	v_lshlrev_b32_e32 v0, 15, v14
	s_cmp_lt_u32 s6, 2
	v_lshl_add_u64 v[156:157], v[4:5], 0, s[2:3]
	s_mov_b32 s2, 0x176e4000
	v_and_b32_e32 v0, 0xffff0000, v0
	s_waitcnt vmcnt(6)
	s_cselect_b32 s2, 0x156e4000, s2
	v_lshl_add_u32 v0, v13, 12, v0
	v_and_b32_e32 v3, 1, v14
	s_add_u32 s46, s22, s2
	v_lshl_or_b32 v0, v3, 6, v0
	v_readlane_b32 s2, v252, 25
	v_or_b32_e32 v170, 0xfffffc00, v2
	s_mov_b32 s67, 0
	s_addc_u32 s47, s23, 0
	v_or_b32_e32 v171, s7, v17
	v_mov_b32_e32 v159, v1
	v_mov_b32_e32 v160, v226
	v_mov_b32_e32 v161, v1
	v_mov_b32_e32 v172, v230
	v_lshlrev_b32_e32 v162, 1, v2
	v_readlane_b32 s72, v252, 14
	s_mov_b32 s4, s2
	s_barrier
	v_readlane_b32 s3, v252, 26
	s_branch .LBB0_344

; #define PG8_STAGE(bufoff, gbase, voff) do { _Pragma("unroll") for (int _i = 0; _i < 2; ++_i) \
;         __builtin_amdgcn_global_load_lds((const unsigned*)((const char*)(gbase) + (voff)[_i]), (PG8_LAS unsigned*)(lds + (bufoff) + ldsw + _i * 8192), 16, 0, 0); } while (0)
; #define PG8_LDA(dst, b, h) do { _Pragma("unroll") for (int m = 0; m < 4; ++m) _Pragma("unroll") for (int k = 0; k < 2; ++k) dst[m][k] = *(const PG8_LAS bf16x8*)(lds + PG8_SA(b, h) + aoff + m * 2048 + k * 1024); } while (0)
; #define PG8_LDB(dst, b, h) do { _Pragma("unroll") for (int n = 0; n < 2; ++n) _Pragma("unroll") for (int k = 0; k < 2; ++k) dst[n][k] = *(const PG8_LAS bf16x8*)(lds + PG8_SB(b, h) + boff + n * 2048 + k * 1024); } while (0)
; #define PG8_MMA(ai, bj, At, Bt) do { __builtin_amdgcn_s_setprio(1); _Pragma("unroll") for (int m = 0; m < 4; ++m) _Pragma("unroll") for (int n = 0; n < 2; ++n) _Pragma("unroll") for (int k = 0; k < 2; ++k) \
;         acc[ai][bj][m][n] = __builtin_amdgcn_mfma_f32_16x16x32_bf16(Bt[n][k], At[m][k], acc[ai][bj][m][n], 0, 0, 0); __builtin_amdgcn_s_setprio(0); } while (0)
; #define PG8_WAIT_V(n) asm volatile("s_waitcnt vmcnt(" #n ")" ::: "memory")
; #define PG8_WAIT_L(n) asm volatile("s_waitcnt lgkmcnt(" #n ")" ::: "memory")
; #define PG8_BAR __builtin_amdgcn_s_barrier()
; #define PG8_SCHED __builtin_amdgcn_sched_barrier(0)
; template <class Epi, class Sched, bool ALIGN_EPI = false, bool SP2 = false>
; __device__ __forceinline__ void gemm_phase(PG8_LAS unsigned char* lds, const Gemm g, const Sched& S, const Epi& E) {
;     ...
;             PG8_LDB(B0, 0, 0); PG8_LDB(B1, 0, 1); PG8_SCHED; PG8_LDA(At, 0, 0); PG8_STAGE(PG8_SA(1, 1), a1 + hstep, voffA);
;             PG8_WAIT_V(8); PG8_WAIT_L(0); PG8_BAR; PG8_MMA(0, 0, At, B0); PG8_MMA(0, 1, At, B1); PG8_BAR; PG8_SCHED;
;             PG8_LDA(At, 0, 1); PG8_STAGE(PG8_SB(0, 0), b2, voffB); PG8_STAGE(PG8_SB(0, 1), b2 + hstep, voffB); PG8_STAGE(PG8_SA(0, 0), a2, voffA);
;             PG8_WAIT_V(8); PG8_WAIT_L(0); PG8_BAR; PG8_MMA(1, 0, At, B0); PG8_MMA(1, 1, At, B1); PG8_BAR; PG8_SCHED;
.LBB0_351:
	s_add_u32 s2, s12, 0xfff80080
	s_addc_u32 s3, s13, -1
	s_add_i32 s20, 0, 0x10000
	s_cmp_eq_u32 s51, 28
	s_cselect_b32 s43, s5, s3
	s_cselect_b32 s42, s6, s2
	v_add_u32_e32 v0, s20, v169
	v_add_u32_e32 v250, s20, v249
	s_cselect_b32 s25, s7, s49
	s_cselect_b32 s24, s8, s9
	s_add_i32 s33, 0, 0x14000
	ds_read_b128 v[2:5], v0
	ds_read_b128 v[6:9], v250
	ds_read_b128 v[138:141], v0 offset:2048
	ds_read_b128 v[142:145], v250 offset:2048
	v_add_u32_e32 v0, s33, v169
	v_add_u32_e32 v251, s33, v249
	ds_read_b128 v[164:167], v0
	ds_read_b128 v[174:177], v251
	ds_read_b128 v[186:189], v0 offset:2048
	ds_read_b128 v[190:193], v251 offset:2048
	s_add_i32 m0, s58, 0xc000
	ds_read_b128 v[194:197], v172
	ds_read_b128 v[198:201], v248
	ds_read_b128 v[202:205], v172 offset:2048
	ds_read_b128 v[206:209], v248 offset:2048
	ds_read_b128 v[210:213], v172 offset:4096
	ds_read_b128 v[214:217], v248 offset:4096
	ds_read_b128 v[218:221], v172 offset:6144
	ds_read_b128 v[222:225], v248 offset:6144
	global_load_lds_dwordx4 v160, s[12:13]
	s_add_i32 m0, s58, 0xe000
	s_nop 0
	global_load_lds_dwordx4 v158, s[12:13]
	s_waitcnt vmcnt(8)
	s_waitcnt lgkmcnt(0)
	s_barrier
	s_setprio 1
	s_waitcnt lgkmcnt(0)
	v_mfma_f32_16x16x32_bf16 v[134:137], v[2:5], v[194:197], v[134:137]
	v_mfma_f32_16x16x32_bf16 v[130:133], v[138:141], v[194:197], v[130:133]
	v_mfma_f32_16x16x32_bf16 v[118:121], v[2:5], v[202:205], v[118:121]
	v_mfma_f32_16x16x32_bf16 v[114:117], v[138:141], v[202:205], v[114:117]
	v_mfma_f32_16x16x32_bf16 v[102:105], v[2:5], v[210:213], v[102:105]
	v_mfma_f32_16x16x32_bf16 v[98:101], v[138:141], v[210:213], v[98:101]
	v_mfma_f32_16x16x32_bf16 v[86:89], v[2:5], v[218:221], v[86:89]
	v_mfma_f32_16x16x32_bf16 v[82:85], v[138:141], v[218:221], v[82:85]
	v_mfma_f32_16x16x32_bf16 v[134:137], v[6:9], v[198:201], v[134:137]
	v_mfma_f32_16x16x32_bf16 v[130:133], v[142:145], v[198:201], v[130:133]
	v_mfma_f32_16x16x32_bf16 v[118:121], v[6:9], v[206:209], v[118:121]
	v_mfma_f32_16x16x32_bf16 v[114:117], v[142:145], v[206:209], v[114:117]
	v_mfma_f32_16x16x32_bf16 v[102:105], v[6:9], v[214:217], v[102:105]
	v_mfma_f32_16x16x32_bf16 v[98:101], v[142:145], v[214:217], v[98:101]
	v_mfma_f32_16x16x32_bf16 v[86:89], v[6:9], v[222:225], v[86:89]
	v_mfma_f32_16x16x32_bf16 v[82:85], v[142:145], v[222:225], v[82:85]
	s_setprio 0
	s_setprio 1
	v_mfma_f32_16x16x32_bf16 v[126:129], v[164:167], v[194:197], v[126:129]
	v_mfma_f32_16x16x32_bf16 v[122:125], v[186:189], v[194:197], v[122:125]
	v_mfma_f32_16x16x32_bf16 v[110:113], v[164:167], v[202:205], v[110:113]
	v_mfma_f32_16x16x32_bf16 v[106:109], v[186:189], v[202:205], v[106:109]
	v_mfma_f32_16x16x32_bf16 v[94:97], v[164:167], v[210:213], v[94:97]
	v_mfma_f32_16x16x32_bf16 v[90:93], v[186:189], v[210:213], v[90:93]
	v_mfma_f32_16x16x32_bf16 v[78:81], v[164:167], v[218:221], v[78:81]
	v_mfma_f32_16x16x32_bf16 v[74:77], v[186:189], v[218:221], v[74:77]
	v_mfma_f32_16x16x32_bf16 v[126:129], v[174:177], v[198:201], v[126:129]
	v_mfma_f32_16x16x32_bf16 v[122:125], v[190:193], v[198:201], v[122:125]
	v_mfma_f32_16x16x32_bf16 v[110:113], v[174:177], v[206:209], v[110:113]
	v_mfma_f32_16x16x32_bf16 v[106:109], v[190:193], v[206:209], v[106:109]
	v_mfma_f32_16x16x32_bf16 v[94:97], v[174:177], v[214:217], v[94:97]
	v_mfma_f32_16x16x32_bf16 v[90:93], v[190:193], v[214:217], v[90:93]
	v_mfma_f32_16x16x32_bf16 v[78:81], v[174:177], v[222:225], v[78:81]
	v_mfma_f32_16x16x32_bf16 v[74:77], v[190:193], v[222:225], v[74:77]
	s_setprio 0
	s_barrier
	s_add_i32 s2, s20, s57
	s_mov_b32 m0, s2
	ds_read_b128 v[194:197], v172 offset:16384
	ds_read_b128 v[198:201], v248 offset:16384
	ds_read_b128 v[202:205], v172 offset:18432
	ds_read_b128 v[206:209], v248 offset:18432
	ds_read_b128 v[210:213], v172 offset:20480
	ds_read_b128 v[214:217], v248 offset:20480
	ds_read_b128 v[218:221], v172 offset:22528
	ds_read_b128 v[222:225], v248 offset:22528
	global_load_lds_dwordx4 v150, s[24:25]
	s_add_i32 m0, s2, 0x2000
	s_add_u32 s2, s24, 0x80000
	s_addc_u32 s3, s25, 0
	s_add_i32 s20, s33, s57
	global_load_lds_dwordx4 v146, s[24:25]
	s_mov_b32 m0, s20
	s_nop 0
	global_load_lds_dwordx4 v150, s[2:3]
	s_add_i32 m0, s20, 0x2000
	s_nop 0
	global_load_lds_dwordx4 v146, s[2:3]
	s_mov_b32 m0, s58
	s_nop 0
	global_load_lds_dwordx4 v152, s[42:43]
	s_mov_b32 m0, s59
	s_nop 0
	global_load_lds_dwordx4 v148, s[42:43]
	s_waitcnt vmcnt(8)
	s_waitcnt lgkmcnt(0)
	s_barrier
	s_setprio 1
	s_waitcnt lgkmcnt(0)
	v_mfma_f32_16x16x32_bf16 v[70:73], v[2:5], v[194:197], v[70:73]
	v_mfma_f32_16x16x32_bf16 v[66:69], v[138:141], v[194:197], v[66:69]
	v_mfma_f32_16x16x32_bf16 v[54:57], v[2:5], v[202:205], v[54:57]
	v_mfma_f32_16x16x32_bf16 v[50:53], v[138:141], v[202:205], v[50:53]
	v_mfma_f32_16x16x32_bf16 v[38:41], v[2:5], v[210:213], v[38:41]
	v_mfma_f32_16x16x32_bf16 v[34:37], v[138:141], v[210:213], v[34:37]
	v_mfma_f32_16x16x32_bf16 v[2:5], v[2:5], v[218:221], v[22:25]
	v_mfma_f32_16x16x32_bf16 v[70:73], v[6:9], v[198:201], v[70:73]
	v_mfma_f32_16x16x32_bf16 v[66:69], v[142:145], v[198:201], v[66:69]
	v_mfma_f32_16x16x32_bf16 v[54:57], v[6:9], v[206:209], v[54:57]
	v_mfma_f32_16x16x32_bf16 v[50:53], v[142:145], v[206:209], v[50:53]
	v_mfma_f32_16x16x32_bf16 v[38:41], v[6:9], v[214:217], v[38:41]
	v_mfma_f32_16x16x32_bf16 v[34:37], v[142:145], v[214:217], v[34:37]
	v_mfma_f32_16x16x32_bf16 v[2:5], v[6:9], v[222:225], v[2:5]
	v_mfma_f32_16x16x32_bf16 v[6:9], v[138:141], v[218:221], v[18:21]
	v_mfma_f32_16x16x32_bf16 v[6:9], v[142:145], v[222:225], v[6:9]
	s_setprio 0
	s_setprio 1
	v_mfma_f32_16x16x32_bf16 v[18:21], v[164:167], v[194:197], v[62:65]
	v_mfma_f32_16x16x32_bf16 v[62:65], v[174:177], v[198:201], v[18:21]
	v_mfma_f32_16x16x32_bf16 v[18:21], v[186:189], v[194:197], v[58:61]
	v_mfma_f32_16x16x32_bf16 v[58:61], v[190:193], v[198:201], v[18:21]
	v_mfma_f32_16x16x32_bf16 v[18:21], v[164:167], v[202:205], v[46:49]
	v_mfma_f32_16x16x32_bf16 v[46:49], v[174:177], v[206:209], v[18:21]
	v_mfma_f32_16x16x32_bf16 v[18:21], v[186:189], v[202:205], v[42:45]
	v_mfma_f32_16x16x32_bf16 v[42:45], v[190:193], v[206:209], v[18:21]
	v_mfma_f32_16x16x32_bf16 v[18:21], v[164:167], v[210:213], v[30:33]
	v_mfma_f32_16x16x32_bf16 v[30:33], v[174:177], v[214:217], v[18:21]
	v_mfma_f32_16x16x32_bf16 v[18:21], v[186:189], v[210:213], v[26:29]
	v_mfma_f32_16x16x32_bf16 v[14:17], v[164:167], v[218:221], v[14:17]
	v_mfma_f32_16x16x32_bf16 v[10:13], v[186:189], v[218:221], v[10:13]
	v_mfma_f32_16x16x32_bf16 v[26:29], v[190:193], v[214:217], v[18:21]
	v_mfma_f32_16x16x32_bf16 v[14:17], v[174:177], v[222:225], v[14:17]
	v_mfma_f32_16x16x32_bf16 v[10:13], v[190:193], v[222:225], v[10:13]
	s_setprio 0
	s_barrier
; #define PG8_STAGE(bufoff, gbase, voff) do { _Pragma("unroll") for (int _i = 0; _i < 2; ++_i) \
;         __builtin_amdgcn_global_load_lds((const unsigned*)((const char*)(gbase) + (voff)[_i]), (PG8_LAS unsigned*)(lds + (bufoff) + ldsw + _i * 8192), 16, 0, 0); } while (0)
; #define PG8_LDA(dst, b, h) do { _Pragma("unroll") for (int m = 0; m < 4; ++m) _Pragma("unroll") for (int k = 0; k < 2; ++k) dst[m][k] = *(const PG8_LAS bf16x8*)(lds + PG8_SA(b, h) + aoff + m * 2048 + k * 1024); } while (0)
; #define PG8_LDB(dst, b, h) do { _Pragma("unroll") for (int n = 0; n < 2; ++n) _Pragma("unroll") for (int k = 0; k < 2; ++k) dst[n][k] = *(const PG8_LAS bf16x8*)(lds + PG8_SB(b, h) + boff + n * 2048 + k * 1024); } while (0)
; #define PG8_MMA(ai, bj, At, Bt) do { __builtin_amdgcn_s_setprio(1); _Pragma("unroll") for (int m = 0; m < 4; ++m) _Pragma("unroll") for (int n = 0; n < 2; ++n) _Pragma("unroll") for (int k = 0; k < 2; ++k) \
;         acc[ai][bj][m][n] = __builtin_amdgcn_mfma_f32_16x16x32_bf16(Bt[n][k], At[m][k], acc[ai][bj][m][n], 0, 0, 0); __builtin_amdgcn_s_setprio(0); } while (0)
; #define PG8_WAIT_V(n) asm volatile("s_waitcnt vmcnt(" #n ")" ::: "memory")
; #define PG8_WAIT_L(n) asm volatile("s_waitcnt lgkmcnt(" #n ")" ::: "memory")
; #define PG8_BAR __builtin_amdgcn_s_barrier()
; #define PG8_SCHED __builtin_amdgcn_sched_barrier(0)
; template <class Epi, class Sched, bool ALIGN_EPI = false, bool SP2 = false>
; __device__ __forceinline__ void gemm_phase(PG8_LAS unsigned char* lds, const Gemm g, const Sched& S, const Epi& E) {
;     ...
;         for (int t = 0; t < nt; t += 2) {
;     ...
;             PG8_LDB(B0, 1, 0); PG8_LDB(B1, 1, 1); PG8_SCHED; PG8_LDA(At, 1, 0); PG8_STAGE(PG8_SA(0, 1), a2 + hstep, voffA);
;             PG8_WAIT_V(8); PG8_WAIT_L(0); PG8_BAR; PG8_MMA(0, 0, At, B0); PG8_MMA(0, 1, At, B1); PG8_BAR; PG8_SCHED;
;             PG8_LDA(At, 1, 1); PG8_STAGE(PG8_SB(1, 0), b3, voffB); PG8_STAGE(PG8_SB(1, 1), b3 + hstep, voffB); PG8_STAGE(PG8_SA(1, 0), a3, voffA);
;             PG8_WAIT_V(8); PG8_WAIT_L(0); PG8_BAR; PG8_MMA(1, 0, At, B0); PG8_MMA(1, 1, At, B1); PG8_BAR; PG8_SCHED;
	s_add_i32 s20, 0, 0x18000
	v_add_u32_e32 v0, s20, v169
	v_add_u32_e32 v250, s20, v249
	s_add_i32 s33, 0, 0x1c000
	ds_read_b128 v[18:21], v0
	ds_read_b128 v[22:25], v250
	ds_read_b128 v[138:141], v0 offset:2048
	ds_read_b128 v[142:145], v250 offset:2048
	v_add_u32_e32 v0, s33, v169
	v_add_u32_e32 v251, s33, v249
	ds_read_b128 v[164:167], v0
	ds_read_b128 v[174:177], v251
	ds_read_b128 v[186:189], v0 offset:2048
	ds_read_b128 v[190:193], v251 offset:2048
	s_add_u32 s2, s42, 0x80000
	s_addc_u32 s3, s43, 0
	s_mov_b32 m0, s60
	ds_read_b128 v[194:197], v172 offset:32768
	ds_read_b128 v[198:201], v248 offset:32768
	ds_read_b128 v[202:205], v172 offset:34816
	ds_read_b128 v[206:209], v248 offset:34816
	ds_read_b128 v[210:213], v172 offset:36864
	ds_read_b128 v[214:217], v248 offset:36864
	ds_read_b128 v[218:221], v172 offset:38912
	ds_read_b128 v[222:225], v248 offset:38912
	global_load_lds_dwordx4 v152, s[2:3]
	s_mov_b32 m0, s61
	s_nop 0
	global_load_lds_dwordx4 v148, s[2:3]
	s_waitcnt vmcnt(8)
	s_waitcnt lgkmcnt(0)
	s_barrier
	s_setprio 1
	s_waitcnt lgkmcnt(0)
	v_mfma_f32_16x16x32_bf16 v[134:137], v[18:21], v[194:197], v[134:137]
	v_mfma_f32_16x16x32_bf16 v[130:133], v[138:141], v[194:197], v[130:133]
	v_mfma_f32_16x16x32_bf16 v[118:121], v[18:21], v[202:205], v[118:121]
	v_mfma_f32_16x16x32_bf16 v[114:117], v[138:141], v[202:205], v[114:117]
	v_mfma_f32_16x16x32_bf16 v[102:105], v[18:21], v[210:213], v[102:105]
	v_mfma_f32_16x16x32_bf16 v[98:101], v[138:141], v[210:213], v[98:101]
	v_mfma_f32_16x16x32_bf16 v[86:89], v[18:21], v[218:221], v[86:89]
	v_mfma_f32_16x16x32_bf16 v[82:85], v[138:141], v[218:221], v[82:85]
	v_mfma_f32_16x16x32_bf16 v[134:137], v[22:25], v[198:201], v[134:137]
	v_mfma_f32_16x16x32_bf16 v[130:133], v[142:145], v[198:201], v[130:133]
	v_mfma_f32_16x16x32_bf16 v[118:121], v[22:25], v[206:209], v[118:121]
	v_mfma_f32_16x16x32_bf16 v[114:117], v[142:145], v[206:209], v[114:117]
	v_mfma_f32_16x16x32_bf16 v[102:105], v[22:25], v[214:217], v[102:105]
	v_mfma_f32_16x16x32_bf16 v[98:101], v[142:145], v[214:217], v[98:101]
	v_mfma_f32_16x16x32_bf16 v[86:89], v[22:25], v[222:225], v[86:89]
	v_mfma_f32_16x16x32_bf16 v[82:85], v[142:145], v[222:225], v[82:85]
	s_setprio 0
	s_setprio 1
	v_mfma_f32_16x16x32_bf16 v[126:129], v[164:167], v[194:197], v[126:129]
	v_mfma_f32_16x16x32_bf16 v[122:125], v[186:189], v[194:197], v[122:125]
	v_mfma_f32_16x16x32_bf16 v[110:113], v[164:167], v[202:205], v[110:113]
	v_mfma_f32_16x16x32_bf16 v[106:109], v[186:189], v[202:205], v[106:109]
	v_mfma_f32_16x16x32_bf16 v[94:97], v[164:167], v[210:213], v[94:97]
	v_mfma_f32_16x16x32_bf16 v[90:93], v[186:189], v[210:213], v[90:93]
	v_mfma_f32_16x16x32_bf16 v[78:81], v[164:167], v[218:221], v[78:81]
	v_mfma_f32_16x16x32_bf16 v[74:77], v[186:189], v[218:221], v[74:77]
	v_mfma_f32_16x16x32_bf16 v[126:129], v[174:177], v[198:201], v[126:129]
	v_mfma_f32_16x16x32_bf16 v[122:125], v[190:193], v[198:201], v[122:125]
	v_mfma_f32_16x16x32_bf16 v[110:113], v[174:177], v[206:209], v[110:113]
	v_mfma_f32_16x16x32_bf16 v[106:109], v[190:193], v[206:209], v[106:109]
	v_mfma_f32_16x16x32_bf16 v[94:97], v[174:177], v[214:217], v[94:97]
	v_mfma_f32_16x16x32_bf16 v[90:93], v[190:193], v[214:217], v[90:93]
	v_mfma_f32_16x16x32_bf16 v[78:81], v[174:177], v[222:225], v[78:81]
	v_mfma_f32_16x16x32_bf16 v[74:77], v[190:193], v[222:225], v[74:77]
	s_setprio 0
	s_barrier
	s_add_i32 s2, s20, s57
	s_add_i32 m0, s2, 0xffffff80
	ds_read_b128 v[194:197], v172 offset:49152
	ds_read_b128 v[198:201], v248 offset:49152
	ds_read_b128 v[202:205], v172 offset:51200
	ds_read_b128 v[206:209], v248 offset:51200
	ds_read_b128 v[210:213], v172 offset:53248
	ds_read_b128 v[214:217], v248 offset:53248
	ds_read_b128 v[218:221], v172 offset:55296
	ds_read_b128 v[222:225], v248 offset:55296
	global_load_lds_dwordx4 v150, s[24:25] offset:128
	s_add_i32 m0, s2, 0x1f80
	s_add_u32 s2, s24, 0x80080
	s_addc_u32 s3, s25, 0
	s_add_i32 s20, s33, s57
	global_load_lds_dwordx4 v146, s[24:25] offset:128
	s_mov_b32 m0, s20
	s_nop 0
	global_load_lds_dwordx4 v150, s[2:3]
	s_add_i32 m0, s20, 0x2000
	s_nop 0
	global_load_lds_dwordx4 v146, s[2:3]
	s_add_i32 m0, s64, 0xffffff80
	s_nop 0
	global_load_lds_dwordx4 v152, s[42:43] offset:128
	s_add_i32 m0, s65, 0xffffff80
	s_nop 0
	global_load_lds_dwordx4 v148, s[42:43] offset:128
	s_waitcnt vmcnt(8)
	s_waitcnt lgkmcnt(0)
	s_barrier
	s_setprio 1
	s_waitcnt lgkmcnt(0)
	v_mfma_f32_16x16x32_bf16 v[70:73], v[18:21], v[194:197], v[70:73]
	v_mfma_f32_16x16x32_bf16 v[54:57], v[18:21], v[202:205], v[54:57]
	v_mfma_f32_16x16x32_bf16 v[38:41], v[18:21], v[210:213], v[38:41]
	v_mfma_f32_16x16x32_bf16 v[2:5], v[18:21], v[218:221], v[2:5]
	v_mfma_f32_16x16x32_bf16 v[70:73], v[22:25], v[198:201], v[70:73]
	v_mfma_f32_16x16x32_bf16 v[66:69], v[138:141], v[194:197], v[66:69]
	v_mfma_f32_16x16x32_bf16 v[54:57], v[22:25], v[206:209], v[54:57]
	v_mfma_f32_16x16x32_bf16 v[50:53], v[138:141], v[202:205], v[50:53]
	v_mfma_f32_16x16x32_bf16 v[38:41], v[22:25], v[214:217], v[38:41]
	v_mfma_f32_16x16x32_bf16 v[34:37], v[138:141], v[210:213], v[34:37]
	v_mfma_f32_16x16x32_bf16 v[22:25], v[22:25], v[222:225], v[2:5]
	v_mfma_f32_16x16x32_bf16 v[2:5], v[138:141], v[218:221], v[6:9]
	v_mfma_f32_16x16x32_bf16 v[66:69], v[142:145], v[198:201], v[66:69]
	v_mfma_f32_16x16x32_bf16 v[50:53], v[142:145], v[206:209], v[50:53]
	v_mfma_f32_16x16x32_bf16 v[34:37], v[142:145], v[214:217], v[34:37]
	v_mfma_f32_16x16x32_bf16 v[18:21], v[142:145], v[222:225], v[2:5]
	s_setprio 0
	s_setprio 1
	v_mfma_f32_16x16x32_bf16 v[2:5], v[164:167], v[194:197], v[62:65]
	v_mfma_f32_16x16x32_bf16 v[62:65], v[174:177], v[198:201], v[2:5]
	v_mfma_f32_16x16x32_bf16 v[2:5], v[186:189], v[194:197], v[58:61]
	v_mfma_f32_16x16x32_bf16 v[58:61], v[190:193], v[198:201], v[2:5]
	v_mfma_f32_16x16x32_bf16 v[2:5], v[164:167], v[202:205], v[46:49]
	v_mfma_f32_16x16x32_bf16 v[46:49], v[174:177], v[206:209], v[2:5]
	v_mfma_f32_16x16x32_bf16 v[2:5], v[186:189], v[202:205], v[42:45]
	v_mfma_f32_16x16x32_bf16 v[42:45], v[190:193], v[206:209], v[2:5]
	v_mfma_f32_16x16x32_bf16 v[2:5], v[164:167], v[210:213], v[30:33]
	v_mfma_f32_16x16x32_bf16 v[30:33], v[174:177], v[214:217], v[2:5]
	v_mfma_f32_16x16x32_bf16 v[2:5], v[186:189], v[210:213], v[26:29]
	v_mfma_f32_16x16x32_bf16 v[26:29], v[190:193], v[214:217], v[2:5]
	v_mfma_f32_16x16x32_bf16 v[2:5], v[164:167], v[218:221], v[14:17]
	v_mfma_f32_16x16x32_bf16 v[14:17], v[174:177], v[222:225], v[2:5]
	v_mfma_f32_16x16x32_bf16 v[2:5], v[186:189], v[218:221], v[10:13]
	v_mfma_f32_16x16x32_bf16 v[10:13], v[190:193], v[222:225], v[2:5]
	s_setprio 0
	s_barrier
	s_add_i32 s51, s51, 2
	s_add_u32 s9, s9, 0x100
	s_addc_u32 s49, s49, 0
	s_add_u32 s12, s12, 0x100
	s_addc_u32 s13, s13, 0
	s_cmp_gt_u32 s51, 29
	s_cbranch_scc0 .LBB0_351
	s_and_b64 vcc, exec, s[26:27]
	s_cbranch_vccz .LBB0_356
	s_barrier
	v_lshl_add_u32 v164, s4, 8, v168
	s_cmp_gt_i32 s72, 7
	s_mov_b64 s[12:13], -1
	s_cbranch_scc1 .LBB0_357
